# GEMM loops: m0-write s_nops removed by reordering m0 write before the DMA address op (on top of static priority)
# baseline (speedup 1.0000x reference)
.Lgout_enter:
.LBB0_128:
	s_add_u32 s14, vcc_lo, 0xfffc0080
	s_addc_u32 s15, vcc_hi, -1
	s_add_i32 s20, 16, 0x10000
	v_add_u32_e32 v130, s20, v160
	ds_read_b128 v[154:157], v130
	ds_read_b128 v[164:167], v130 offset:1024
	ds_read_b128 v[168:171], v130 offset:2048
	ds_read_b128 v[172:175], v130 offset:3072
	s_cmp_eq_u32 s34, 12
	s_cselect_b32 s19, s0, s15
	s_cselect_b32 s18, s1, s14
	s_cselect_b32 s15, s13, s31
	s_cselect_b32 s14, s24, s25
	v_lshl_add_u64 v[130:131], vcc, 0, v[150:151]
	s_add_i32 m0, s9, 0xc000
	ds_read_b128 v[176:179], v162
	ds_read_b128 v[180:183], v162 offset:1024
	ds_read_b128 v[184:187], v162 offset:2048
	ds_read_b128 v[188:191], v162 offset:3072
	ds_read_b128 v[192:195], v162 offset:4096
	ds_read_b128 v[196:199], v162 offset:5120
	ds_read_b128 v[200:203], v162 offset:6144
	ds_read_b128 v[204:207], v162 offset:7168
	global_load_lds_dwordx4 v[130:131], off
	s_add_i32 m0, s9, 0xe000
	v_lshl_add_u64 v[130:131], vcc, 0, v[152:153]
	global_load_lds_dwordx4 v[130:131], off
	s_add_i32 s35, 16, 0x14000
	v_add_u32_e32 v130, s35, v160
	ds_read_b128 v[208:211], v130
	ds_read_b128 v[212:215], v130 offset:1024
	ds_read_b128 v[216:219], v130 offset:2048
	ds_read_b128 v[220:223], v130 offset:3072
	s_waitcnt vmcnt(8) lgkmcnt(0)
	s_barrier
	v_mfma_f32_16x16x32_bf16 v[124:127], v[154:157], v[176:179], v[124:127]
	v_mfma_f32_16x16x32_bf16 v[120:123], v[168:171], v[176:179], v[120:123]
	v_mfma_f32_16x16x32_bf16 v[108:111], v[154:157], v[184:187], v[108:111]
	v_mfma_f32_16x16x32_bf16 v[104:107], v[168:171], v[184:187], v[104:107]
	v_mfma_f32_16x16x32_bf16 v[92:95], v[154:157], v[192:195], v[92:95]
	v_mfma_f32_16x16x32_bf16 v[88:91], v[168:171], v[192:195], v[88:91]
	v_mfma_f32_16x16x32_bf16 v[76:79], v[154:157], v[200:203], v[76:79]
	v_mfma_f32_16x16x32_bf16 v[72:75], v[168:171], v[200:203], v[72:75]
	v_mfma_f32_16x16x32_bf16 v[124:127], v[164:167], v[180:183], v[124:127]
	v_mfma_f32_16x16x32_bf16 v[120:123], v[172:175], v[180:183], v[120:123]
	v_mfma_f32_16x16x32_bf16 v[108:111], v[164:167], v[188:191], v[108:111]
	v_mfma_f32_16x16x32_bf16 v[104:107], v[172:175], v[188:191], v[104:107]
	v_mfma_f32_16x16x32_bf16 v[92:95], v[164:167], v[196:199], v[92:95]
	v_mfma_f32_16x16x32_bf16 v[88:91], v[172:175], v[196:199], v[88:91]
	v_mfma_f32_16x16x32_bf16 v[76:79], v[164:167], v[204:207], v[76:79]
	v_mfma_f32_16x16x32_bf16 v[72:75], v[172:175], v[204:207], v[72:75]
	v_mfma_f32_16x16x32_bf16 v[116:119], v[208:211], v[176:179], v[116:119]
	v_mfma_f32_16x16x32_bf16 v[112:115], v[216:219], v[176:179], v[112:115]
	v_mfma_f32_16x16x32_bf16 v[100:103], v[208:211], v[184:187], v[100:103]
	v_mfma_f32_16x16x32_bf16 v[96:99], v[216:219], v[184:187], v[96:99]
	v_mfma_f32_16x16x32_bf16 v[84:87], v[208:211], v[192:195], v[84:87]
	v_mfma_f32_16x16x32_bf16 v[80:83], v[216:219], v[192:195], v[80:83]
	v_mfma_f32_16x16x32_bf16 v[68:71], v[208:211], v[200:203], v[68:71]
	v_mfma_f32_16x16x32_bf16 v[64:67], v[216:219], v[200:203], v[64:67]
	v_mfma_f32_16x16x32_bf16 v[116:119], v[212:215], v[180:183], v[116:119]
	v_mfma_f32_16x16x32_bf16 v[112:115], v[220:223], v[180:183], v[112:115]
	v_mfma_f32_16x16x32_bf16 v[100:103], v[212:215], v[188:191], v[100:103]
	v_mfma_f32_16x16x32_bf16 v[96:99], v[220:223], v[188:191], v[96:99]
	v_mfma_f32_16x16x32_bf16 v[84:87], v[212:215], v[196:199], v[84:87]
	v_mfma_f32_16x16x32_bf16 v[80:83], v[220:223], v[196:199], v[80:83]
	v_mfma_f32_16x16x32_bf16 v[68:71], v[212:215], v[204:207], v[68:71]
	v_mfma_f32_16x16x32_bf16 v[64:67], v[220:223], v[204:207], v[64:67]
	s_barrier
	ds_read_b128 v[176:179], v162 offset:16384
	ds_read_b128 v[180:183], v162 offset:17408
	ds_read_b128 v[184:187], v162 offset:18432
	ds_read_b128 v[188:191], v162 offset:19456
	ds_read_b128 v[192:195], v162 offset:20480
	ds_read_b128 v[196:199], v162 offset:21504
	ds_read_b128 v[200:203], v162 offset:22528
	ds_read_b128 v[204:207], v162 offset:23552
	s_add_i32 s20, s20, s5
	v_lshl_add_u64 v[130:131], s[14:15], 0, v[128:129]
	s_mov_b32 m0, s20
	v_lshl_add_u64 v[132:133], s[14:15], 0, v[148:149]
	global_load_lds_dwordx4 v[130:131], off
	s_add_i32 m0, s20, 0x2000
	s_nop 0
	global_load_lds_dwordx4 v[132:133], off
	s_mov_b32 m0, s9
	v_lshl_add_u64 v[134:135], s[18:19], 0, v[144:145]
	global_load_lds_dwordx4 v[134:135], off
	s_mov_b32 m0, s36
	v_lshl_add_u64 v[136:137], s[18:19], 0, v[146:147]
	global_load_lds_dwordx4 v[136:137], off
	s_add_u32 s48, s14, 0x40000
	s_addc_u32 s49, s15, 0
	s_add_i32 s20, s35, s5
	s_mov_b32 m0, s20
	v_lshl_add_u64 v[138:139], s[48:49], 0, v[128:129]
	global_load_lds_dwordx4 v[138:139], off
	s_add_i32 m0, s20, 0x2000
	v_lshl_add_u64 v[138:139], s[48:49], 0, v[148:149]
	global_load_lds_dwordx4 v[138:139], off
	s_waitcnt vmcnt(8) lgkmcnt(0)
	s_barrier
	v_mfma_f32_16x16x32_bf16 v[60:63], v[154:157], v[176:179], v[60:63]
	v_mfma_f32_16x16x32_bf16 v[56:59], v[168:171], v[176:179], v[56:59]
	v_mfma_f32_16x16x32_bf16 v[44:47], v[154:157], v[184:187], v[44:47]
	v_mfma_f32_16x16x32_bf16 v[40:43], v[168:171], v[184:187], v[40:43]
	v_mfma_f32_16x16x32_bf16 v[28:31], v[154:157], v[192:195], v[28:31]
	v_mfma_f32_16x16x32_bf16 v[24:27], v[168:171], v[192:195], v[24:27]
	v_mfma_f32_16x16x32_bf16 v[12:15], v[154:157], v[200:203], v[12:15]
	v_mfma_f32_16x16x32_bf16 v[8:11], v[168:171], v[200:203], v[8:11]
	v_mfma_f32_16x16x32_bf16 v[60:63], v[164:167], v[180:183], v[60:63]
	v_mfma_f32_16x16x32_bf16 v[56:59], v[172:175], v[180:183], v[56:59]
	v_mfma_f32_16x16x32_bf16 v[44:47], v[164:167], v[188:191], v[44:47]
	v_mfma_f32_16x16x32_bf16 v[40:43], v[172:175], v[188:191], v[40:43]
	v_mfma_f32_16x16x32_bf16 v[28:31], v[164:167], v[196:199], v[28:31]
	v_mfma_f32_16x16x32_bf16 v[24:27], v[172:175], v[196:199], v[24:27]
	v_mfma_f32_16x16x32_bf16 v[12:15], v[164:167], v[204:207], v[12:15]
	v_mfma_f32_16x16x32_bf16 v[8:11], v[172:175], v[204:207], v[8:11]
	v_mfma_f32_16x16x32_bf16 v[52:55], v[208:211], v[176:179], v[52:55]
	v_mfma_f32_16x16x32_bf16 v[48:51], v[216:219], v[176:179], v[48:51]
	v_mfma_f32_16x16x32_bf16 v[36:39], v[208:211], v[184:187], v[36:39]
	v_mfma_f32_16x16x32_bf16 v[32:35], v[216:219], v[184:187], v[32:35]
	v_mfma_f32_16x16x32_bf16 v[20:23], v[208:211], v[192:195], v[20:23]
	v_mfma_f32_16x16x32_bf16 v[16:19], v[216:219], v[192:195], v[16:19]
	v_mfma_f32_16x16x32_bf16 v[4:7], v[208:211], v[200:203], v[4:7]
	v_mfma_f32_16x16x32_bf16 v[0:3], v[216:219], v[200:203], v[0:3]
	v_mfma_f32_16x16x32_bf16 v[52:55], v[212:215], v[180:183], v[52:55]
	v_mfma_f32_16x16x32_bf16 v[48:51], v[220:223], v[180:183], v[48:51]
	v_mfma_f32_16x16x32_bf16 v[36:39], v[212:215], v[188:191], v[36:39]
	v_mfma_f32_16x16x32_bf16 v[32:35], v[220:223], v[188:191], v[32:35]
	v_mfma_f32_16x16x32_bf16 v[20:23], v[212:215], v[196:199], v[20:23]
	v_mfma_f32_16x16x32_bf16 v[16:19], v[220:223], v[196:199], v[16:19]
	v_mfma_f32_16x16x32_bf16 v[4:7], v[212:215], v[204:207], v[4:7]
	v_mfma_f32_16x16x32_bf16 v[0:3], v[220:223], v[204:207], v[0:3]
	s_add_i32 s20, 16, 0x18000
	v_add_u32_e32 v138, s20, v160
	s_barrier
	ds_read_b128 v[154:157], v138
	ds_read_b128 v[164:167], v138 offset:1024
	ds_read_b128 v[168:171], v138 offset:2048
	ds_read_b128 v[172:175], v138 offset:3072
	s_add_u32 s18, s18, 0x40000
	s_addc_u32 s19, s19, 0
	s_mov_b32 m0, s37
	v_lshl_add_u64 v[158:159], s[18:19], 0, v[144:145]
	ds_read_b128 v[176:179], v162 offset:32768
	ds_read_b128 v[180:183], v162 offset:33792
	ds_read_b128 v[184:187], v162 offset:34816
	ds_read_b128 v[188:191], v162 offset:35840
	ds_read_b128 v[192:195], v162 offset:36864
	ds_read_b128 v[196:199], v162 offset:37888
	ds_read_b128 v[200:203], v162 offset:38912
	ds_read_b128 v[204:207], v162 offset:39936
	global_load_lds_dwordx4 v[158:159], off
	s_mov_b32 m0, s46
	v_lshl_add_u64 v[158:159], s[18:19], 0, v[146:147]
	global_load_lds_dwordx4 v[158:159], off
	s_add_i32 s18, 16, 0x1c000
	v_add_u32_e32 v138, s18, v160
	ds_read_b128 v[208:211], v138
	ds_read_b128 v[212:215], v138 offset:1024
	ds_read_b128 v[216:219], v138 offset:2048
	ds_read_b128 v[220:223], v138 offset:3072
	s_waitcnt vmcnt(8) lgkmcnt(0)
	s_barrier
	v_mfma_f32_16x16x32_bf16 v[124:127], v[154:157], v[176:179], v[124:127]
	v_mfma_f32_16x16x32_bf16 v[120:123], v[168:171], v[176:179], v[120:123]
	v_mfma_f32_16x16x32_bf16 v[108:111], v[154:157], v[184:187], v[108:111]
	v_mfma_f32_16x16x32_bf16 v[104:107], v[168:171], v[184:187], v[104:107]
	v_mfma_f32_16x16x32_bf16 v[92:95], v[154:157], v[192:195], v[92:95]
	v_mfma_f32_16x16x32_bf16 v[88:91], v[168:171], v[192:195], v[88:91]
	v_mfma_f32_16x16x32_bf16 v[76:79], v[154:157], v[200:203], v[76:79]
	v_mfma_f32_16x16x32_bf16 v[72:75], v[168:171], v[200:203], v[72:75]
	v_mfma_f32_16x16x32_bf16 v[124:127], v[164:167], v[180:183], v[124:127]
	v_mfma_f32_16x16x32_bf16 v[120:123], v[172:175], v[180:183], v[120:123]
	v_mfma_f32_16x16x32_bf16 v[108:111], v[164:167], v[188:191], v[108:111]
	v_mfma_f32_16x16x32_bf16 v[104:107], v[172:175], v[188:191], v[104:107]
	v_mfma_f32_16x16x32_bf16 v[92:95], v[164:167], v[196:199], v[92:95]
	v_mfma_f32_16x16x32_bf16 v[88:91], v[172:175], v[196:199], v[88:91]
	v_mfma_f32_16x16x32_bf16 v[76:79], v[164:167], v[204:207], v[76:79]
	v_mfma_f32_16x16x32_bf16 v[72:75], v[172:175], v[204:207], v[72:75]
	v_mfma_f32_16x16x32_bf16 v[116:119], v[208:211], v[176:179], v[116:119]
	v_mfma_f32_16x16x32_bf16 v[112:115], v[216:219], v[176:179], v[112:115]
	v_mfma_f32_16x16x32_bf16 v[100:103], v[208:211], v[184:187], v[100:103]
	v_mfma_f32_16x16x32_bf16 v[96:99], v[216:219], v[184:187], v[96:99]
	v_mfma_f32_16x16x32_bf16 v[84:87], v[208:211], v[192:195], v[84:87]
	v_mfma_f32_16x16x32_bf16 v[80:83], v[216:219], v[192:195], v[80:83]
	v_mfma_f32_16x16x32_bf16 v[68:71], v[208:211], v[200:203], v[68:71]
	v_mfma_f32_16x16x32_bf16 v[64:67], v[216:219], v[200:203], v[64:67]
	v_mfma_f32_16x16x32_bf16 v[116:119], v[212:215], v[180:183], v[116:119]
	v_mfma_f32_16x16x32_bf16 v[112:115], v[220:223], v[180:183], v[112:115]
	v_mfma_f32_16x16x32_bf16 v[100:103], v[212:215], v[188:191], v[100:103]
	v_mfma_f32_16x16x32_bf16 v[96:99], v[220:223], v[188:191], v[96:99]
	v_mfma_f32_16x16x32_bf16 v[84:87], v[212:215], v[196:199], v[84:87]
	v_mfma_f32_16x16x32_bf16 v[80:83], v[220:223], v[196:199], v[80:83]
	v_mfma_f32_16x16x32_bf16 v[68:71], v[212:215], v[204:207], v[68:71]
	v_mfma_f32_16x16x32_bf16 v[64:67], v[220:223], v[204:207], v[64:67]
	s_barrier
	ds_read_b128 v[176:179], v162 offset:49152
	ds_read_b128 v[180:183], v162 offset:50176
	ds_read_b128 v[184:187], v162 offset:51200
	ds_read_b128 v[188:191], v162 offset:52224
	ds_read_b128 v[192:195], v162 offset:53248
	ds_read_b128 v[196:199], v162 offset:54272
	ds_read_b128 v[200:203], v162 offset:55296
	ds_read_b128 v[204:207], v162 offset:56320
	s_add_i32 s19, s20, s5
	s_mov_b32 m0, s19
	v_lshl_add_u64 v[130:131], v[130:131], 0, s[28:29]
	global_load_lds_dwordx4 v[130:131], off
	s_add_i32 m0, s19, 0x2000
	v_lshl_add_u64 v[130:131], v[132:133], 0, s[28:29]
	global_load_lds_dwordx4 v[130:131], off
	s_mov_b32 m0, s47
	v_lshl_add_u64 v[130:131], v[134:135], 0, s[28:29]
	global_load_lds_dwordx4 v[130:131], off
	s_mov_b32 m0, s92
	v_lshl_add_u64 v[130:131], v[136:137], 0, s[28:29]
	global_load_lds_dwordx4 v[130:131], off
	s_add_u32 s14, s14, 0x40080
	s_addc_u32 s15, s15, 0
	s_add_i32 s18, s18, s5
	s_mov_b32 m0, s18
	v_lshl_add_u64 v[130:131], s[14:15], 0, v[128:129]
	global_load_lds_dwordx4 v[130:131], off
	s_add_i32 m0, s18, 0x2000
	v_lshl_add_u64 v[130:131], s[14:15], 0, v[148:149]
	global_load_lds_dwordx4 v[130:131], off
	s_waitcnt vmcnt(8) lgkmcnt(0)
	s_barrier
	v_mfma_f32_16x16x32_bf16 v[60:63], v[154:157], v[176:179], v[60:63]
	v_mfma_f32_16x16x32_bf16 v[56:59], v[168:171], v[176:179], v[56:59]
	v_mfma_f32_16x16x32_bf16 v[44:47], v[154:157], v[184:187], v[44:47]
	v_mfma_f32_16x16x32_bf16 v[40:43], v[168:171], v[184:187], v[40:43]
	v_mfma_f32_16x16x32_bf16 v[28:31], v[154:157], v[192:195], v[28:31]
	v_mfma_f32_16x16x32_bf16 v[24:27], v[168:171], v[192:195], v[24:27]
	v_mfma_f32_16x16x32_bf16 v[12:15], v[154:157], v[200:203], v[12:15]
	v_mfma_f32_16x16x32_bf16 v[8:11], v[168:171], v[200:203], v[8:11]
	v_mfma_f32_16x16x32_bf16 v[60:63], v[164:167], v[180:183], v[60:63]
	v_mfma_f32_16x16x32_bf16 v[56:59], v[172:175], v[180:183], v[56:59]
	v_mfma_f32_16x16x32_bf16 v[44:47], v[164:167], v[188:191], v[44:47]
	v_mfma_f32_16x16x32_bf16 v[40:43], v[172:175], v[188:191], v[40:43]
	v_mfma_f32_16x16x32_bf16 v[28:31], v[164:167], v[196:199], v[28:31]
	v_mfma_f32_16x16x32_bf16 v[24:27], v[172:175], v[196:199], v[24:27]
	v_mfma_f32_16x16x32_bf16 v[12:15], v[164:167], v[204:207], v[12:15]
	v_mfma_f32_16x16x32_bf16 v[8:11], v[172:175], v[204:207], v[8:11]
	v_mfma_f32_16x16x32_bf16 v[52:55], v[208:211], v[176:179], v[52:55]
	v_mfma_f32_16x16x32_bf16 v[48:51], v[216:219], v[176:179], v[48:51]
	v_mfma_f32_16x16x32_bf16 v[36:39], v[208:211], v[184:187], v[36:39]
	v_mfma_f32_16x16x32_bf16 v[32:35], v[216:219], v[184:187], v[32:35]
	v_mfma_f32_16x16x32_bf16 v[20:23], v[208:211], v[192:195], v[20:23]
	v_mfma_f32_16x16x32_bf16 v[16:19], v[216:219], v[192:195], v[16:19]
	v_mfma_f32_16x16x32_bf16 v[4:7], v[208:211], v[200:203], v[4:7]
	v_mfma_f32_16x16x32_bf16 v[0:3], v[216:219], v[200:203], v[0:3]
	v_mfma_f32_16x16x32_bf16 v[52:55], v[212:215], v[180:183], v[52:55]
	v_mfma_f32_16x16x32_bf16 v[48:51], v[220:223], v[180:183], v[48:51]
	v_mfma_f32_16x16x32_bf16 v[36:39], v[212:215], v[188:191], v[36:39]
	v_mfma_f32_16x16x32_bf16 v[32:35], v[220:223], v[188:191], v[32:35]
	v_mfma_f32_16x16x32_bf16 v[20:23], v[212:215], v[196:199], v[20:23]
	v_mfma_f32_16x16x32_bf16 v[16:19], v[220:223], v[196:199], v[16:19]
	v_mfma_f32_16x16x32_bf16 v[4:7], v[212:215], v[204:207], v[4:7]
	v_mfma_f32_16x16x32_bf16 v[0:3], v[220:223], v[204:207], v[0:3]
	s_add_i32 s34, s34, 2
	s_add_u32 vcc_lo, vcc_lo, 0x100
	s_addc_u32 vcc_hi, vcc_hi, 0
	s_add_u32 s25, s25, 0x100
	s_addc_u32 s31, s31, 0
	s_cmp_gt_u32 s34, 13
	s_cbranch_scc1 .Lgout_exit
	s_barrier
	s_branch .LBB0_128

.Lgout_epi:
	s_setprio 0
	s_nop 0
	s_nop 0
	s_nop 0
	s_nop 0
	s_nop 0
	s_nop 0
	s_nop 0
	s_nop 0
	s_nop 0
	s_nop 0
	s_nop 0
	s_nop 0
	s_nop 0
	s_nop 0
	s_nop 0
	s_nop 0
	s_cmp_lt_i32 s8, 0
	s_cselect_b64 s[14:15], -1, 0
	s_cmp_gt_i32 s8, -1
	s_cbranch_scc1 .LBB0_131
	v_mul_f32_e32 v131, 0x3d372713, v120
	v_mul_f32_e32 v131, v120, v131
	v_fma_f32 v131, v120, v131, v120
	v_mul_f32_e32 v131, 0x3fcc422a, v131
	v_mul_f32_e32 v131, 0xbfb8aa3b, v131
	v_exp_f32_e32 v131, v131
	v_mul_f32_e32 v130, 0x3d372713, v124
	v_mul_f32_e32 v130, v124, v130
	v_fma_f32 v130, v124, v130, v124
	v_add_f32_e32 v131, 1.0, v131
	v_rcp_f32_e32 v132, v131
	v_mul_f32_e32 v131, 0x3d372713, v125
	v_mul_f32_e32 v131, v125, v131
	v_fma_f32 v131, v125, v131, v125
	v_mul_f32_e32 v130, 0x3fcc422a, v130
	v_mul_f32_e32 v131, 0x3fcc422a, v131
	v_mul_f32_e32 v130, 0xbfb8aa3b, v130
	v_mul_f32_e32 v131, 0xbfb8aa3b, v131
	v_mul_f32_e32 v135, 0x3d372713, v122
	v_exp_f32_e32 v130, v130
	v_exp_f32_e32 v131, v131
	v_mul_f32_e32 v135, v122, v135
	v_fma_f32 v135, v122, v135, v122
	v_mul_f32_e32 v135, 0x3fcc422a, v135
	v_mul_f32_e32 v135, 0xbfb8aa3b, v135
	v_add_f32_e32 v130, 1.0, v130
	v_add_f32_e32 v131, 1.0, v131
	v_exp_f32_e32 v135, v135
	v_rcp_f32_e32 v130, v130
	v_rcp_f32_e32 v131, v131
	v_mul_f32_e32 v133, 0x3d372713, v121
	v_add_f32_e32 v135, 1.0, v135
	v_mul_f32_e32 v134, 0x3d372713, v126
	v_rcp_f32_e32 v136, v135
	v_mul_f32_e32 v135, 0x3d372713, v127
	v_pk_mul_f32 v[124:125], v[124:125], v[130:131]
	v_mul_f32_e32 v130, 0x3d372713, v123
	v_mul_f32_e32 v133, v121, v133
	v_mul_f32_e32 v134, v126, v134
	v_mul_f32_e32 v135, v127, v135
	v_mul_f32_e32 v130, v123, v130
	v_fma_f32 v133, v121, v133, v121
	v_fma_f32 v134, v126, v134, v126
	v_fma_f32 v135, v127, v135, v127
	v_fma_f32 v130, v123, v130, v123
	v_mul_f32_e32 v133, 0x3fcc422a, v133
	v_mul_f32_e32 v134, 0x3fcc422a, v134
	v_mul_f32_e32 v135, 0x3fcc422a, v135
	v_mul_f32_e32 v130, 0x3fcc422a, v130
	v_mul_f32_e32 v133, 0xbfb8aa3b, v133
	v_mul_f32_e32 v134, 0xbfb8aa3b, v134
	v_mul_f32_e32 v135, 0xbfb8aa3b, v135
	v_mul_f32_e32 v130, 0xbfb8aa3b, v130
	v_exp_f32_e32 v133, v133
	v_exp_f32_e32 v134, v134
	v_exp_f32_e32 v135, v135
	v_exp_f32_e32 v130, v130
	v_add_f32_e32 v133, 1.0, v133
	v_add_f32_e32 v134, 1.0, v134
	v_add_f32_e32 v135, 1.0, v135
	v_add_f32_e32 v130, 1.0, v130
	v_rcp_f32_e32 v133, v133
	v_rcp_f32_e32 v134, v134
	v_rcp_f32_e32 v135, v135
	v_rcp_f32_e32 v137, v130
	v_pk_mul_f32 v[120:121], v[120:121], v[132:133]
	v_pk_mul_f32 v[126:127], v[126:127], v[134:135]
	v_pk_mul_f32 v[122:123], v[122:123], v[136:137]

.Lgin_enter:
.LBB0_271:
	s_add_u32 s14, s30, 0xfffc0080
	s_addc_u32 s15, s31, -1
	s_add_i32 s20, 16, 0x10000
	v_add_u32_e32 v130, s20, v162
	ds_read_b128 v[158:161], v130
	ds_read_b128 v[172:175], v130 offset:1024
	ds_read_b128 v[176:179], v130 offset:2048
	ds_read_b128 v[180:183], v130 offset:3072
	s_cmp_eq_u32 s25, 12
	s_cselect_b32 s19, s0, s15
	s_cselect_b32 s18, s1, s14
	s_cselect_b32 s15, s9, s24
	s_cselect_b32 s14, s13, s17
	v_lshl_add_u64 v[130:131], s[30:31], 0, v[150:151]
	s_add_i32 m0, s5, 0xc000
	ds_read_b128 v[184:187], v164
	ds_read_b128 v[188:191], v164 offset:1024
	ds_read_b128 v[192:195], v164 offset:2048
	ds_read_b128 v[196:199], v164 offset:3072
	ds_read_b128 v[200:203], v164 offset:4096
	ds_read_b128 v[204:207], v164 offset:5120
	ds_read_b128 v[208:211], v164 offset:6144
	ds_read_b128 v[212:215], v164 offset:7168
	global_load_lds_dwordx4 v[130:131], off
	s_add_i32 m0, s5, 0xe000
	v_lshl_add_u64 v[130:131], s[30:31], 0, v[152:153]
	global_load_lds_dwordx4 v[130:131], off
	s_add_i32 s41, 16, 0x14000
	v_add_u32_e32 v130, s41, v162
	ds_read_b128 v[216:219], v130
	ds_read_b128 v[220:223], v130 offset:1024
	ds_read_b128 v[224:227], v130 offset:2048
	ds_read_b128 v[228:231], v130 offset:3072
	s_waitcnt vmcnt(8) lgkmcnt(0)
	s_barrier
	v_mfma_f32_16x16x32_bf16 v[124:127], v[158:161], v[184:187], v[124:127]
	v_mfma_f32_16x16x32_bf16 v[120:123], v[176:179], v[184:187], v[120:123]
	v_mfma_f32_16x16x32_bf16 v[108:111], v[158:161], v[192:195], v[108:111]
	v_mfma_f32_16x16x32_bf16 v[104:107], v[176:179], v[192:195], v[104:107]
	v_mfma_f32_16x16x32_bf16 v[92:95], v[158:161], v[200:203], v[92:95]
	v_mfma_f32_16x16x32_bf16 v[88:91], v[176:179], v[200:203], v[88:91]
	v_mfma_f32_16x16x32_bf16 v[76:79], v[158:161], v[208:211], v[76:79]
	v_mfma_f32_16x16x32_bf16 v[72:75], v[176:179], v[208:211], v[72:75]
	v_mfma_f32_16x16x32_bf16 v[124:127], v[172:175], v[188:191], v[124:127]
	v_mfma_f32_16x16x32_bf16 v[120:123], v[180:183], v[188:191], v[120:123]
	v_mfma_f32_16x16x32_bf16 v[108:111], v[172:175], v[196:199], v[108:111]
	v_mfma_f32_16x16x32_bf16 v[104:107], v[180:183], v[196:199], v[104:107]
	v_mfma_f32_16x16x32_bf16 v[92:95], v[172:175], v[204:207], v[92:95]
	v_mfma_f32_16x16x32_bf16 v[88:91], v[180:183], v[204:207], v[88:91]
	v_mfma_f32_16x16x32_bf16 v[76:79], v[172:175], v[212:215], v[76:79]
	v_mfma_f32_16x16x32_bf16 v[72:75], v[180:183], v[212:215], v[72:75]
	v_mfma_f32_16x16x32_bf16 v[116:119], v[216:219], v[184:187], v[116:119]
	v_mfma_f32_16x16x32_bf16 v[112:115], v[224:227], v[184:187], v[112:115]
	v_mfma_f32_16x16x32_bf16 v[100:103], v[216:219], v[192:195], v[100:103]
	v_mfma_f32_16x16x32_bf16 v[96:99], v[224:227], v[192:195], v[96:99]
	v_mfma_f32_16x16x32_bf16 v[84:87], v[216:219], v[200:203], v[84:87]
	v_mfma_f32_16x16x32_bf16 v[80:83], v[224:227], v[200:203], v[80:83]
	v_mfma_f32_16x16x32_bf16 v[68:71], v[216:219], v[208:211], v[68:71]
	v_mfma_f32_16x16x32_bf16 v[64:67], v[224:227], v[208:211], v[64:67]
	v_mfma_f32_16x16x32_bf16 v[116:119], v[220:223], v[188:191], v[116:119]
	v_mfma_f32_16x16x32_bf16 v[112:115], v[228:231], v[188:191], v[112:115]
	v_mfma_f32_16x16x32_bf16 v[100:103], v[220:223], v[196:199], v[100:103]
	v_mfma_f32_16x16x32_bf16 v[96:99], v[228:231], v[196:199], v[96:99]
	v_mfma_f32_16x16x32_bf16 v[84:87], v[220:223], v[204:207], v[84:87]
	v_mfma_f32_16x16x32_bf16 v[80:83], v[228:231], v[204:207], v[80:83]
	v_mfma_f32_16x16x32_bf16 v[68:71], v[220:223], v[212:215], v[68:71]
	v_mfma_f32_16x16x32_bf16 v[64:67], v[228:231], v[212:215], v[64:67]
	s_barrier
	ds_read_b128 v[184:187], v164 offset:16384
	ds_read_b128 v[188:191], v164 offset:17408
	ds_read_b128 v[192:195], v164 offset:18432
	ds_read_b128 v[196:199], v164 offset:19456
	ds_read_b128 v[200:203], v164 offset:20480
	ds_read_b128 v[204:207], v164 offset:21504
	ds_read_b128 v[208:211], v164 offset:22528
	ds_read_b128 v[212:215], v164 offset:23552
	s_add_i32 s20, s20, s92
	v_lshl_add_u64 v[130:131], s[14:15], 0, v[128:129]
	s_mov_b32 m0, s20
	v_lshl_add_u64 v[132:133], s[14:15], 0, v[148:149]
	global_load_lds_dwordx4 v[130:131], off
	s_add_i32 m0, s20, 0x2000
	s_nop 0
	global_load_lds_dwordx4 v[132:133], off
	s_mov_b32 m0, s5
	v_lshl_add_u64 v[134:135], s[18:19], 0, v[144:145]
	global_load_lds_dwordx4 v[134:135], off
	s_mov_b32 m0, s4
	v_lshl_add_u64 v[136:137], s[18:19], 0, v[146:147]
	global_load_lds_dwordx4 v[136:137], off
	s_add_u32 s34, s14, 0x40000
	s_addc_u32 s35, s15, 0
	s_add_i32 s20, s41, s92
	s_mov_b32 m0, s20
	v_lshl_add_u64 v[138:139], s[34:35], 0, v[128:129]
	global_load_lds_dwordx4 v[138:139], off
	s_add_i32 m0, s20, 0x2000
	v_lshl_add_u64 v[138:139], s[34:35], 0, v[148:149]
	global_load_lds_dwordx4 v[138:139], off
	s_waitcnt vmcnt(8) lgkmcnt(0)
	s_barrier
	v_mfma_f32_16x16x32_bf16 v[60:63], v[158:161], v[184:187], v[60:63]
	v_mfma_f32_16x16x32_bf16 v[56:59], v[176:179], v[184:187], v[56:59]
	v_mfma_f32_16x16x32_bf16 v[44:47], v[158:161], v[192:195], v[44:47]
	v_mfma_f32_16x16x32_bf16 v[40:43], v[176:179], v[192:195], v[40:43]
	v_mfma_f32_16x16x32_bf16 v[28:31], v[158:161], v[200:203], v[28:31]
	v_mfma_f32_16x16x32_bf16 v[24:27], v[176:179], v[200:203], v[24:27]
	v_mfma_f32_16x16x32_bf16 v[12:15], v[158:161], v[208:211], v[12:15]
	v_mfma_f32_16x16x32_bf16 v[8:11], v[176:179], v[208:211], v[8:11]
	v_mfma_f32_16x16x32_bf16 v[60:63], v[172:175], v[188:191], v[60:63]
	v_mfma_f32_16x16x32_bf16 v[56:59], v[180:183], v[188:191], v[56:59]
	v_mfma_f32_16x16x32_bf16 v[44:47], v[172:175], v[196:199], v[44:47]
	v_mfma_f32_16x16x32_bf16 v[40:43], v[180:183], v[196:199], v[40:43]
	v_mfma_f32_16x16x32_bf16 v[28:31], v[172:175], v[204:207], v[28:31]
	v_mfma_f32_16x16x32_bf16 v[24:27], v[180:183], v[204:207], v[24:27]
	v_mfma_f32_16x16x32_bf16 v[12:15], v[172:175], v[212:215], v[12:15]
	v_mfma_f32_16x16x32_bf16 v[8:11], v[180:183], v[212:215], v[8:11]
	v_mfma_f32_16x16x32_bf16 v[52:55], v[216:219], v[184:187], v[52:55]
	v_mfma_f32_16x16x32_bf16 v[48:51], v[224:227], v[184:187], v[48:51]
	v_mfma_f32_16x16x32_bf16 v[36:39], v[216:219], v[192:195], v[36:39]
	v_mfma_f32_16x16x32_bf16 v[32:35], v[224:227], v[192:195], v[32:35]
	v_mfma_f32_16x16x32_bf16 v[20:23], v[216:219], v[200:203], v[20:23]
	v_mfma_f32_16x16x32_bf16 v[16:19], v[224:227], v[200:203], v[16:19]
	v_mfma_f32_16x16x32_bf16 v[4:7], v[216:219], v[208:211], v[4:7]
	v_mfma_f32_16x16x32_bf16 v[0:3], v[224:227], v[208:211], v[0:3]
	v_mfma_f32_16x16x32_bf16 v[52:55], v[220:223], v[188:191], v[52:55]
	v_mfma_f32_16x16x32_bf16 v[48:51], v[228:231], v[188:191], v[48:51]
	v_mfma_f32_16x16x32_bf16 v[36:39], v[220:223], v[196:199], v[36:39]
	v_mfma_f32_16x16x32_bf16 v[32:35], v[228:231], v[196:199], v[32:35]
	v_mfma_f32_16x16x32_bf16 v[20:23], v[220:223], v[204:207], v[20:23]
	v_mfma_f32_16x16x32_bf16 v[16:19], v[228:231], v[204:207], v[16:19]
	v_mfma_f32_16x16x32_bf16 v[4:7], v[220:223], v[212:215], v[4:7]
	v_mfma_f32_16x16x32_bf16 v[0:3], v[228:231], v[212:215], v[0:3]
	s_add_i32 s20, 16, 0x18000
	v_add_u32_e32 v138, s20, v162
	s_barrier
	ds_read_b128 v[158:161], v138
	ds_read_b128 v[172:175], v138 offset:1024
	ds_read_b128 v[176:179], v138 offset:2048
	ds_read_b128 v[180:183], v138 offset:3072
	s_add_u32 s18, s18, 0x40000
	s_addc_u32 s19, s19, 0
	s_mov_b32 m0, s36
	v_lshl_add_u64 v[216:217], s[18:19], 0, v[144:145]
	ds_read_b128 v[184:187], v164 offset:32768
	ds_read_b128 v[188:191], v164 offset:33792
	ds_read_b128 v[192:195], v164 offset:34816
	ds_read_b128 v[196:199], v164 offset:35840
	ds_read_b128 v[200:203], v164 offset:36864
	ds_read_b128 v[204:207], v164 offset:37888
	ds_read_b128 v[208:211], v164 offset:38912
	ds_read_b128 v[212:215], v164 offset:39936
	global_load_lds_dwordx4 v[216:217], off
	s_mov_b32 m0, s37
	v_lshl_add_u64 v[216:217], s[18:19], 0, v[146:147]
	global_load_lds_dwordx4 v[216:217], off
	s_add_i32 s18, 16, 0x1c000
	v_add_u32_e32 v138, s18, v162
	ds_read_b128 v[216:219], v138
	ds_read_b128 v[220:223], v138 offset:1024
	ds_read_b128 v[224:227], v138 offset:2048
	ds_read_b128 v[228:231], v138 offset:3072
	s_waitcnt vmcnt(8) lgkmcnt(0)
	s_barrier
	v_mfma_f32_16x16x32_bf16 v[124:127], v[158:161], v[184:187], v[124:127]
	v_mfma_f32_16x16x32_bf16 v[120:123], v[176:179], v[184:187], v[120:123]
	v_mfma_f32_16x16x32_bf16 v[108:111], v[158:161], v[192:195], v[108:111]
	v_mfma_f32_16x16x32_bf16 v[104:107], v[176:179], v[192:195], v[104:107]
	v_mfma_f32_16x16x32_bf16 v[92:95], v[158:161], v[200:203], v[92:95]
	v_mfma_f32_16x16x32_bf16 v[88:91], v[176:179], v[200:203], v[88:91]
	v_mfma_f32_16x16x32_bf16 v[76:79], v[158:161], v[208:211], v[76:79]
	v_mfma_f32_16x16x32_bf16 v[72:75], v[176:179], v[208:211], v[72:75]
	v_mfma_f32_16x16x32_bf16 v[124:127], v[172:175], v[188:191], v[124:127]
	v_mfma_f32_16x16x32_bf16 v[120:123], v[180:183], v[188:191], v[120:123]
	v_mfma_f32_16x16x32_bf16 v[108:111], v[172:175], v[196:199], v[108:111]
	v_mfma_f32_16x16x32_bf16 v[104:107], v[180:183], v[196:199], v[104:107]
	v_mfma_f32_16x16x32_bf16 v[92:95], v[172:175], v[204:207], v[92:95]
	v_mfma_f32_16x16x32_bf16 v[88:91], v[180:183], v[204:207], v[88:91]
	v_mfma_f32_16x16x32_bf16 v[76:79], v[172:175], v[212:215], v[76:79]
	v_mfma_f32_16x16x32_bf16 v[72:75], v[180:183], v[212:215], v[72:75]
	v_mfma_f32_16x16x32_bf16 v[116:119], v[216:219], v[184:187], v[116:119]
	v_mfma_f32_16x16x32_bf16 v[112:115], v[224:227], v[184:187], v[112:115]
	v_mfma_f32_16x16x32_bf16 v[100:103], v[216:219], v[192:195], v[100:103]
	v_mfma_f32_16x16x32_bf16 v[96:99], v[224:227], v[192:195], v[96:99]
	v_mfma_f32_16x16x32_bf16 v[84:87], v[216:219], v[200:203], v[84:87]
	v_mfma_f32_16x16x32_bf16 v[80:83], v[224:227], v[200:203], v[80:83]
	v_mfma_f32_16x16x32_bf16 v[68:71], v[216:219], v[208:211], v[68:71]
	v_mfma_f32_16x16x32_bf16 v[64:67], v[224:227], v[208:211], v[64:67]
	v_mfma_f32_16x16x32_bf16 v[116:119], v[220:223], v[188:191], v[116:119]
	v_mfma_f32_16x16x32_bf16 v[112:115], v[228:231], v[188:191], v[112:115]
	v_mfma_f32_16x16x32_bf16 v[100:103], v[220:223], v[196:199], v[100:103]
	v_mfma_f32_16x16x32_bf16 v[96:99], v[228:231], v[196:199], v[96:99]
	v_mfma_f32_16x16x32_bf16 v[84:87], v[220:223], v[204:207], v[84:87]
	v_mfma_f32_16x16x32_bf16 v[80:83], v[228:231], v[204:207], v[80:83]
	v_mfma_f32_16x16x32_bf16 v[68:71], v[220:223], v[212:215], v[68:71]
	v_mfma_f32_16x16x32_bf16 v[64:67], v[228:231], v[212:215], v[64:67]
	s_barrier
	ds_read_b128 v[184:187], v164 offset:49152
	ds_read_b128 v[188:191], v164 offset:50176
	ds_read_b128 v[192:195], v164 offset:51200
	ds_read_b128 v[196:199], v164 offset:52224
	ds_read_b128 v[200:203], v164 offset:53248
	ds_read_b128 v[204:207], v164 offset:54272
	ds_read_b128 v[208:211], v164 offset:55296
	ds_read_b128 v[212:215], v164 offset:56320
	s_add_i32 s19, s20, s92
	s_mov_b32 m0, s19
	v_lshl_add_u64 v[130:131], v[130:131], 0, s[28:29]
	global_load_lds_dwordx4 v[130:131], off
	s_add_i32 m0, s19, 0x2000
	v_lshl_add_u64 v[130:131], v[132:133], 0, s[28:29]
	global_load_lds_dwordx4 v[130:131], off
	s_mov_b32 m0, s46
	v_lshl_add_u64 v[130:131], v[134:135], 0, s[28:29]
	global_load_lds_dwordx4 v[130:131], off
	s_mov_b32 m0, s47
	v_lshl_add_u64 v[130:131], v[136:137], 0, s[28:29]
	global_load_lds_dwordx4 v[130:131], off
	s_add_u32 s14, s14, 0x40080
	s_addc_u32 s15, s15, 0
	s_add_i32 s18, s18, s92
	s_mov_b32 m0, s18
	v_lshl_add_u64 v[130:131], s[14:15], 0, v[128:129]
	global_load_lds_dwordx4 v[130:131], off
	s_add_i32 m0, s18, 0x2000
	v_lshl_add_u64 v[130:131], s[14:15], 0, v[148:149]
	global_load_lds_dwordx4 v[130:131], off
	s_waitcnt vmcnt(8) lgkmcnt(0)
	s_barrier
	v_mfma_f32_16x16x32_bf16 v[60:63], v[158:161], v[184:187], v[60:63]
	v_mfma_f32_16x16x32_bf16 v[56:59], v[176:179], v[184:187], v[56:59]
	v_mfma_f32_16x16x32_bf16 v[44:47], v[158:161], v[192:195], v[44:47]
	v_mfma_f32_16x16x32_bf16 v[40:43], v[176:179], v[192:195], v[40:43]
	v_mfma_f32_16x16x32_bf16 v[28:31], v[158:161], v[200:203], v[28:31]
	v_mfma_f32_16x16x32_bf16 v[24:27], v[176:179], v[200:203], v[24:27]
	v_mfma_f32_16x16x32_bf16 v[12:15], v[158:161], v[208:211], v[12:15]
	v_mfma_f32_16x16x32_bf16 v[8:11], v[176:179], v[208:211], v[8:11]
	v_mfma_f32_16x16x32_bf16 v[60:63], v[172:175], v[188:191], v[60:63]
	v_mfma_f32_16x16x32_bf16 v[56:59], v[180:183], v[188:191], v[56:59]
	v_mfma_f32_16x16x32_bf16 v[44:47], v[172:175], v[196:199], v[44:47]
	v_mfma_f32_16x16x32_bf16 v[40:43], v[180:183], v[196:199], v[40:43]
	v_mfma_f32_16x16x32_bf16 v[28:31], v[172:175], v[204:207], v[28:31]
	v_mfma_f32_16x16x32_bf16 v[24:27], v[180:183], v[204:207], v[24:27]
	v_mfma_f32_16x16x32_bf16 v[12:15], v[172:175], v[212:215], v[12:15]
	v_mfma_f32_16x16x32_bf16 v[8:11], v[180:183], v[212:215], v[8:11]
	v_mfma_f32_16x16x32_bf16 v[52:55], v[216:219], v[184:187], v[52:55]
	v_mfma_f32_16x16x32_bf16 v[48:51], v[224:227], v[184:187], v[48:51]
	v_mfma_f32_16x16x32_bf16 v[36:39], v[216:219], v[192:195], v[36:39]
	v_mfma_f32_16x16x32_bf16 v[32:35], v[224:227], v[192:195], v[32:35]
	v_mfma_f32_16x16x32_bf16 v[20:23], v[216:219], v[200:203], v[20:23]
	v_mfma_f32_16x16x32_bf16 v[16:19], v[224:227], v[200:203], v[16:19]
	v_mfma_f32_16x16x32_bf16 v[4:7], v[216:219], v[208:211], v[4:7]
	v_mfma_f32_16x16x32_bf16 v[0:3], v[224:227], v[208:211], v[0:3]
	v_mfma_f32_16x16x32_bf16 v[52:55], v[220:223], v[188:191], v[52:55]
	v_mfma_f32_16x16x32_bf16 v[48:51], v[228:231], v[188:191], v[48:51]
	v_mfma_f32_16x16x32_bf16 v[36:39], v[220:223], v[196:199], v[36:39]
	v_mfma_f32_16x16x32_bf16 v[32:35], v[228:231], v[196:199], v[32:35]
	v_mfma_f32_16x16x32_bf16 v[20:23], v[220:223], v[204:207], v[20:23]
	v_mfma_f32_16x16x32_bf16 v[16:19], v[228:231], v[204:207], v[16:19]
	v_mfma_f32_16x16x32_bf16 v[4:7], v[220:223], v[212:215], v[4:7]
	v_mfma_f32_16x16x32_bf16 v[0:3], v[228:231], v[212:215], v[0:3]
	s_add_i32 s25, s25, 2
	s_add_u32 s30, s30, 0x100
	s_addc_u32 s31, s31, 0
	s_add_u32 s17, s17, 0x100
	s_addc_u32 s24, s24, 0
	s_cmp_gt_u32 s25, 13
	s_cbranch_scc1 .Lgin_exit
	s_barrier
	s_branch .LBB0_271

.Lgin_epi:
	s_setprio 0
	s_nop 0
	s_nop 0
	s_nop 0
	s_nop 0
	s_nop 0
	s_nop 0
	s_nop 0
	s_nop 0
	s_nop 0
	s_nop 0
	s_nop 0
	s_nop 0
	s_nop 0
	s_nop 0
	s_nop 0
	s_nop 0
	s_waitcnt vmcnt(0)
	v_fmamk_f32 v130, v156, 0x3a800000, v235
	v_mul_f32_e32 v131, 0x4b800000, v130
	v_cmp_gt_f32_e32 vcc, s86, v130
	s_cmp_lt_i32 s40, 4
	s_cselect_b64 s[14:15], -1, 0
	v_cndmask_b32_e32 v130, v130, v131, vcc
	v_rsq_f32_e32 v130, v130
	s_cmp_gt_i32 s40, 3
	v_mul_f32_e32 v131, 0x45800000, v130
	v_cndmask_b32_e32 v156, v130, v131, vcc
	v_pk_mul_f32 v[126:127], v[156:157], v[126:127] op_sel_hi:[0,1]
	v_pk_mul_f32 v[124:125], v[156:157], v[124:125] op_sel_hi:[0,1]
	v_pk_mul_f32 v[158:159], v[156:157], v[122:123] op_sel_hi:[0,1]
	v_pk_mul_f32 v[160:161], v[156:157], v[120:121] op_sel_hi:[0,1]
	s_cbranch_scc1 .LBB0_274
	v_mul_f32_e32 v121, 0x3d372713, v160
	v_mul_f32_e32 v121, v160, v121
	v_fma_f32 v121, v160, v121, v160
	v_mul_f32_e32 v121, 0x3fcc422a, v121
	v_mul_f32_e32 v121, 0xbfb8aa3b, v121
	v_exp_f32_e32 v121, v121
	v_mul_f32_e32 v120, 0x3d372713, v124
	v_mul_f32_e32 v120, v124, v120
	v_mov_b32_e32 v123, v125
	v_add_f32_e32 v121, 1.0, v121
	v_rcp_f32_e32 v122, v121
	v_mul_f32_e32 v121, 0x3d372713, v125
	v_mul_f32_e32 v121, v125, v121
	v_fma_f32 v120, v124, v120, v124
	v_fmac_f32_e32 v123, v123, v121
	v_mul_f32_e32 v120, 0x3fcc422a, v120
	v_mul_f32_e32 v121, 0x3fcc422a, v123
	v_mul_f32_e32 v120, 0xbfb8aa3b, v120
	v_mul_f32_e32 v121, 0xbfb8aa3b, v121
	v_mul_f32_e32 v131, 0x3d372713, v158
	v_exp_f32_e32 v120, v120
	v_exp_f32_e32 v121, v121
	v_mul_f32_e32 v131, v158, v131
	v_fma_f32 v131, v158, v131, v158
	v_mul_f32_e32 v131, 0x3fcc422a, v131
	v_mul_f32_e32 v131, 0xbfb8aa3b, v131
	v_add_f32_e32 v120, 1.0, v120
	v_add_f32_e32 v121, 1.0, v121
	v_exp_f32_e32 v131, v131
	v_rcp_f32_e32 v120, v120
	v_rcp_f32_e32 v121, v121
	v_mul_f32_e32 v123, 0x3d372713, v161
	v_mul_f32_e32 v123, v161, v123
	v_mov_b32_e32 v130, v161
	v_fmac_f32_e32 v130, v130, v123
	v_add_f32_e32 v131, 1.0, v131
	v_mul_f32_e32 v123, 0x3fcc422a, v130
	v_mul_f32_e32 v130, 0x3d372713, v126
	v_rcp_f32_e32 v132, v131
	v_mul_f32_e32 v131, 0x3d372713, v127
	v_pk_mul_f32 v[124:125], v[124:125], v[120:121]
	v_mul_f32_e32 v120, 0x3d372713, v159
	v_mul_f32_e32 v130, v126, v130
	v_mul_f32_e32 v131, v127, v131
	v_mul_f32_e32 v120, v159, v120
	v_fma_f32 v130, v126, v130, v126
	v_fma_f32 v131, v127, v131, v127
	v_fma_f32 v120, v159, v120, v159
	v_mul_f32_e32 v130, 0x3fcc422a, v130
	v_mul_f32_e32 v131, 0x3fcc422a, v131
	v_mul_f32_e32 v120, 0x3fcc422a, v120
	v_mul_f32_e32 v123, 0xbfb8aa3b, v123
	v_mul_f32_e32 v130, 0xbfb8aa3b, v130
	v_mul_f32_e32 v131, 0xbfb8aa3b, v131
	v_mul_f32_e32 v120, 0xbfb8aa3b, v120
	v_exp_f32_e32 v123, v123
	v_exp_f32_e32 v130, v130
	v_exp_f32_e32 v131, v131
	v_exp_f32_e32 v120, v120
	v_add_f32_e32 v123, 1.0, v123
	v_add_f32_e32 v130, 1.0, v130
	v_add_f32_e32 v131, 1.0, v131
	v_add_f32_e32 v120, 1.0, v120
	v_rcp_f32_e32 v123, v123
	v_rcp_f32_e32 v130, v130
	v_rcp_f32_e32 v131, v131
	v_rcp_f32_e32 v133, v120
	v_pk_mul_f32 v[160:161], v[160:161], v[122:123]
	v_pk_mul_f32 v[126:127], v[126:127], v[130:131]
	v_pk_mul_f32 v[158:159], v[158:159], v[132:133]

.Lg2_enter:
.LBB0_345:
	s_add_u32 s14, s30, 0xfff50080
	s_addc_u32 s15, s31, -1
	s_add_i32 s20, 16, 0x10000
	v_add_u32_e32 v130, s20, v160
	ds_read_b128 v[154:157], v130
	ds_read_b128 v[164:167], v130 offset:1024
	ds_read_b128 v[168:171], v130 offset:2048
	ds_read_b128 v[172:175], v130 offset:3072
	s_cmp_eq_u32 s25, 40
	s_cselect_b32 s19, s9, s15
	s_cselect_b32 s18, s8, s14
	s_cselect_b32 s15, s13, s1
	s_cselect_b32 s14, s12, s0
	v_lshl_add_u64 v[130:131], s[30:31], 0, v[150:151]
	s_add_i32 m0, s34, 0xc000
	ds_read_b128 v[176:179], v162
	ds_read_b128 v[180:183], v162 offset:1024
	ds_read_b128 v[184:187], v162 offset:2048
	ds_read_b128 v[188:191], v162 offset:3072
	ds_read_b128 v[192:195], v162 offset:4096
	ds_read_b128 v[196:199], v162 offset:5120
	ds_read_b128 v[200:203], v162 offset:6144
	ds_read_b128 v[204:207], v162 offset:7168
	global_load_lds_dwordx4 v[130:131], off
	s_add_i32 m0, s34, 0xe000
	v_lshl_add_u64 v[130:131], s[30:31], 0, v[152:153]
	global_load_lds_dwordx4 v[130:131], off
	s_add_i32 s42, 16, 0x14000
	v_add_u32_e32 v130, s42, v160
	ds_read_b128 v[208:211], v130
	ds_read_b128 v[212:215], v130 offset:1024
	ds_read_b128 v[216:219], v130 offset:2048
	ds_read_b128 v[220:223], v130 offset:3072
	s_waitcnt vmcnt(8) lgkmcnt(0)
	s_barrier
	v_mfma_f32_16x16x32_bf16 v[124:127], v[154:157], v[176:179], v[124:127]
	v_mfma_f32_16x16x32_bf16 v[120:123], v[168:171], v[176:179], v[120:123]
	v_mfma_f32_16x16x32_bf16 v[108:111], v[154:157], v[184:187], v[108:111]
	v_mfma_f32_16x16x32_bf16 v[104:107], v[168:171], v[184:187], v[104:107]
	v_mfma_f32_16x16x32_bf16 v[92:95], v[154:157], v[192:195], v[92:95]
	v_mfma_f32_16x16x32_bf16 v[88:91], v[168:171], v[192:195], v[88:91]
	v_mfma_f32_16x16x32_bf16 v[76:79], v[154:157], v[200:203], v[76:79]
	v_mfma_f32_16x16x32_bf16 v[72:75], v[168:171], v[200:203], v[72:75]
	v_mfma_f32_16x16x32_bf16 v[124:127], v[164:167], v[180:183], v[124:127]
	v_mfma_f32_16x16x32_bf16 v[120:123], v[172:175], v[180:183], v[120:123]
	v_mfma_f32_16x16x32_bf16 v[108:111], v[164:167], v[188:191], v[108:111]
	v_mfma_f32_16x16x32_bf16 v[104:107], v[172:175], v[188:191], v[104:107]
	v_mfma_f32_16x16x32_bf16 v[92:95], v[164:167], v[196:199], v[92:95]
	v_mfma_f32_16x16x32_bf16 v[88:91], v[172:175], v[196:199], v[88:91]
	v_mfma_f32_16x16x32_bf16 v[76:79], v[164:167], v[204:207], v[76:79]
	v_mfma_f32_16x16x32_bf16 v[72:75], v[172:175], v[204:207], v[72:75]
	v_mfma_f32_16x16x32_bf16 v[116:119], v[208:211], v[176:179], v[116:119]
	v_mfma_f32_16x16x32_bf16 v[112:115], v[216:219], v[176:179], v[112:115]
	v_mfma_f32_16x16x32_bf16 v[100:103], v[208:211], v[184:187], v[100:103]
	v_mfma_f32_16x16x32_bf16 v[96:99], v[216:219], v[184:187], v[96:99]
	v_mfma_f32_16x16x32_bf16 v[84:87], v[208:211], v[192:195], v[84:87]
	v_mfma_f32_16x16x32_bf16 v[80:83], v[216:219], v[192:195], v[80:83]
	v_mfma_f32_16x16x32_bf16 v[68:71], v[208:211], v[200:203], v[68:71]
	v_mfma_f32_16x16x32_bf16 v[64:67], v[216:219], v[200:203], v[64:67]
	v_mfma_f32_16x16x32_bf16 v[116:119], v[212:215], v[180:183], v[116:119]
	v_mfma_f32_16x16x32_bf16 v[112:115], v[220:223], v[180:183], v[112:115]
	v_mfma_f32_16x16x32_bf16 v[100:103], v[212:215], v[188:191], v[100:103]
	v_mfma_f32_16x16x32_bf16 v[96:99], v[220:223], v[188:191], v[96:99]
	v_mfma_f32_16x16x32_bf16 v[84:87], v[212:215], v[196:199], v[84:87]
	v_mfma_f32_16x16x32_bf16 v[80:83], v[220:223], v[196:199], v[80:83]
	v_mfma_f32_16x16x32_bf16 v[68:71], v[212:215], v[204:207], v[68:71]
	v_mfma_f32_16x16x32_bf16 v[64:67], v[220:223], v[204:207], v[64:67]
	s_barrier
	ds_read_b128 v[176:179], v162 offset:16384
	ds_read_b128 v[180:183], v162 offset:17408
	ds_read_b128 v[184:187], v162 offset:18432
	ds_read_b128 v[188:191], v162 offset:19456
	ds_read_b128 v[192:195], v162 offset:20480
	ds_read_b128 v[196:199], v162 offset:21504
	ds_read_b128 v[200:203], v162 offset:22528
	ds_read_b128 v[204:207], v162 offset:23552
	s_add_i32 s20, s20, s5
	v_lshl_add_u64 v[130:131], s[14:15], 0, v[128:129]
	s_mov_b32 m0, s20
	v_lshl_add_u64 v[132:133], s[14:15], 0, v[148:149]
	global_load_lds_dwordx4 v[130:131], off
	s_add_i32 m0, s20, 0x2000
	s_nop 0
	global_load_lds_dwordx4 v[132:133], off
	s_mov_b32 m0, s34
	v_lshl_add_u64 v[134:135], s[18:19], 0, v[144:145]
	global_load_lds_dwordx4 v[134:135], off
	s_mov_b32 m0, s35
	v_lshl_add_u64 v[136:137], s[18:19], 0, v[146:147]
	global_load_lds_dwordx4 v[136:137], off
	s_add_u32 s40, s14, 0xb0000
	s_addc_u32 s41, s15, 0
	s_add_i32 s20, s42, s5
	s_mov_b32 m0, s20
	v_lshl_add_u64 v[138:139], s[40:41], 0, v[128:129]
	global_load_lds_dwordx4 v[138:139], off
	s_add_i32 m0, s20, 0x2000
	v_lshl_add_u64 v[138:139], s[40:41], 0, v[148:149]
	global_load_lds_dwordx4 v[138:139], off
	s_waitcnt vmcnt(8) lgkmcnt(0)
	s_barrier
	v_mfma_f32_16x16x32_bf16 v[60:63], v[154:157], v[176:179], v[60:63]
	v_mfma_f32_16x16x32_bf16 v[56:59], v[168:171], v[176:179], v[56:59]
	v_mfma_f32_16x16x32_bf16 v[44:47], v[154:157], v[184:187], v[44:47]
	v_mfma_f32_16x16x32_bf16 v[40:43], v[168:171], v[184:187], v[40:43]
	v_mfma_f32_16x16x32_bf16 v[28:31], v[154:157], v[192:195], v[28:31]
	v_mfma_f32_16x16x32_bf16 v[24:27], v[168:171], v[192:195], v[24:27]
	v_mfma_f32_16x16x32_bf16 v[12:15], v[154:157], v[200:203], v[12:15]
	v_mfma_f32_16x16x32_bf16 v[8:11], v[168:171], v[200:203], v[8:11]
	v_mfma_f32_16x16x32_bf16 v[60:63], v[164:167], v[180:183], v[60:63]
	v_mfma_f32_16x16x32_bf16 v[56:59], v[172:175], v[180:183], v[56:59]
	v_mfma_f32_16x16x32_bf16 v[44:47], v[164:167], v[188:191], v[44:47]
	v_mfma_f32_16x16x32_bf16 v[40:43], v[172:175], v[188:191], v[40:43]
	v_mfma_f32_16x16x32_bf16 v[28:31], v[164:167], v[196:199], v[28:31]
	v_mfma_f32_16x16x32_bf16 v[24:27], v[172:175], v[196:199], v[24:27]
	v_mfma_f32_16x16x32_bf16 v[12:15], v[164:167], v[204:207], v[12:15]
	v_mfma_f32_16x16x32_bf16 v[8:11], v[172:175], v[204:207], v[8:11]
	v_mfma_f32_16x16x32_bf16 v[52:55], v[208:211], v[176:179], v[52:55]
	v_mfma_f32_16x16x32_bf16 v[48:51], v[216:219], v[176:179], v[48:51]
	v_mfma_f32_16x16x32_bf16 v[36:39], v[208:211], v[184:187], v[36:39]
	v_mfma_f32_16x16x32_bf16 v[32:35], v[216:219], v[184:187], v[32:35]
	v_mfma_f32_16x16x32_bf16 v[20:23], v[208:211], v[192:195], v[20:23]
	v_mfma_f32_16x16x32_bf16 v[16:19], v[216:219], v[192:195], v[16:19]
	v_mfma_f32_16x16x32_bf16 v[4:7], v[208:211], v[200:203], v[4:7]
	v_mfma_f32_16x16x32_bf16 v[0:3], v[216:219], v[200:203], v[0:3]
	v_mfma_f32_16x16x32_bf16 v[52:55], v[212:215], v[180:183], v[52:55]
	v_mfma_f32_16x16x32_bf16 v[48:51], v[220:223], v[180:183], v[48:51]
	v_mfma_f32_16x16x32_bf16 v[36:39], v[212:215], v[188:191], v[36:39]
	v_mfma_f32_16x16x32_bf16 v[32:35], v[220:223], v[188:191], v[32:35]
	v_mfma_f32_16x16x32_bf16 v[20:23], v[212:215], v[196:199], v[20:23]
	v_mfma_f32_16x16x32_bf16 v[16:19], v[220:223], v[196:199], v[16:19]
	v_mfma_f32_16x16x32_bf16 v[4:7], v[212:215], v[204:207], v[4:7]
	v_mfma_f32_16x16x32_bf16 v[0:3], v[220:223], v[204:207], v[0:3]
	s_add_i32 s20, 16, 0x18000
	v_add_u32_e32 v138, s20, v160
	s_barrier
	ds_read_b128 v[154:157], v138
	ds_read_b128 v[164:167], v138 offset:1024
	ds_read_b128 v[168:171], v138 offset:2048
	ds_read_b128 v[172:175], v138 offset:3072
	s_add_u32 s18, s18, 0xb0000
	s_addc_u32 s19, s19, 0
	s_mov_b32 m0, s36
	v_lshl_add_u64 v[158:159], s[18:19], 0, v[144:145]
	ds_read_b128 v[176:179], v162 offset:32768
	ds_read_b128 v[180:183], v162 offset:33792
	ds_read_b128 v[184:187], v162 offset:34816
	ds_read_b128 v[188:191], v162 offset:35840
	ds_read_b128 v[192:195], v162 offset:36864
	ds_read_b128 v[196:199], v162 offset:37888
	ds_read_b128 v[200:203], v162 offset:38912
	ds_read_b128 v[204:207], v162 offset:39936
	global_load_lds_dwordx4 v[158:159], off
	s_mov_b32 m0, s37
	v_lshl_add_u64 v[158:159], s[18:19], 0, v[146:147]
	global_load_lds_dwordx4 v[158:159], off
	s_add_i32 s18, 16, 0x1c000
	v_add_u32_e32 v138, s18, v160
	ds_read_b128 v[208:211], v138
	ds_read_b128 v[212:215], v138 offset:1024
	ds_read_b128 v[216:219], v138 offset:2048
	ds_read_b128 v[220:223], v138 offset:3072
	s_waitcnt vmcnt(8) lgkmcnt(0)
	s_barrier
	v_mfma_f32_16x16x32_bf16 v[124:127], v[154:157], v[176:179], v[124:127]
	v_mfma_f32_16x16x32_bf16 v[120:123], v[168:171], v[176:179], v[120:123]
	v_mfma_f32_16x16x32_bf16 v[108:111], v[154:157], v[184:187], v[108:111]
	v_mfma_f32_16x16x32_bf16 v[104:107], v[168:171], v[184:187], v[104:107]
	v_mfma_f32_16x16x32_bf16 v[92:95], v[154:157], v[192:195], v[92:95]
	v_mfma_f32_16x16x32_bf16 v[88:91], v[168:171], v[192:195], v[88:91]
	v_mfma_f32_16x16x32_bf16 v[76:79], v[154:157], v[200:203], v[76:79]
	v_mfma_f32_16x16x32_bf16 v[72:75], v[168:171], v[200:203], v[72:75]
	v_mfma_f32_16x16x32_bf16 v[124:127], v[164:167], v[180:183], v[124:127]
	v_mfma_f32_16x16x32_bf16 v[120:123], v[172:175], v[180:183], v[120:123]
	v_mfma_f32_16x16x32_bf16 v[108:111], v[164:167], v[188:191], v[108:111]
	v_mfma_f32_16x16x32_bf16 v[104:107], v[172:175], v[188:191], v[104:107]
	v_mfma_f32_16x16x32_bf16 v[92:95], v[164:167], v[196:199], v[92:95]
	v_mfma_f32_16x16x32_bf16 v[88:91], v[172:175], v[196:199], v[88:91]
	v_mfma_f32_16x16x32_bf16 v[76:79], v[164:167], v[204:207], v[76:79]
	v_mfma_f32_16x16x32_bf16 v[72:75], v[172:175], v[204:207], v[72:75]
	v_mfma_f32_16x16x32_bf16 v[116:119], v[208:211], v[176:179], v[116:119]
	v_mfma_f32_16x16x32_bf16 v[112:115], v[216:219], v[176:179], v[112:115]
	v_mfma_f32_16x16x32_bf16 v[100:103], v[208:211], v[184:187], v[100:103]
	v_mfma_f32_16x16x32_bf16 v[96:99], v[216:219], v[184:187], v[96:99]
	v_mfma_f32_16x16x32_bf16 v[84:87], v[208:211], v[192:195], v[84:87]
	v_mfma_f32_16x16x32_bf16 v[80:83], v[216:219], v[192:195], v[80:83]
	v_mfma_f32_16x16x32_bf16 v[68:71], v[208:211], v[200:203], v[68:71]
	v_mfma_f32_16x16x32_bf16 v[64:67], v[216:219], v[200:203], v[64:67]
	v_mfma_f32_16x16x32_bf16 v[116:119], v[212:215], v[180:183], v[116:119]
	v_mfma_f32_16x16x32_bf16 v[112:115], v[220:223], v[180:183], v[112:115]
	v_mfma_f32_16x16x32_bf16 v[100:103], v[212:215], v[188:191], v[100:103]
	v_mfma_f32_16x16x32_bf16 v[96:99], v[220:223], v[188:191], v[96:99]
	v_mfma_f32_16x16x32_bf16 v[84:87], v[212:215], v[196:199], v[84:87]
	v_mfma_f32_16x16x32_bf16 v[80:83], v[220:223], v[196:199], v[80:83]
	v_mfma_f32_16x16x32_bf16 v[68:71], v[212:215], v[204:207], v[68:71]
	v_mfma_f32_16x16x32_bf16 v[64:67], v[220:223], v[204:207], v[64:67]
	s_barrier
	ds_read_b128 v[176:179], v162 offset:49152
	ds_read_b128 v[180:183], v162 offset:50176
	ds_read_b128 v[184:187], v162 offset:51200
	ds_read_b128 v[188:191], v162 offset:52224
	ds_read_b128 v[192:195], v162 offset:53248
	ds_read_b128 v[196:199], v162 offset:54272
	ds_read_b128 v[200:203], v162 offset:55296
	ds_read_b128 v[204:207], v162 offset:56320
	s_add_i32 s19, s20, s5
	s_mov_b32 m0, s19
	v_lshl_add_u64 v[130:131], v[130:131], 0, s[28:29]
	global_load_lds_dwordx4 v[130:131], off
	s_add_i32 m0, s19, 0x2000
	v_lshl_add_u64 v[130:131], v[132:133], 0, s[28:29]
	global_load_lds_dwordx4 v[130:131], off
	s_mov_b32 m0, s44
	v_lshl_add_u64 v[130:131], v[134:135], 0, s[28:29]
	global_load_lds_dwordx4 v[130:131], off
	s_mov_b32 m0, s45
	v_lshl_add_u64 v[130:131], v[136:137], 0, s[28:29]
	global_load_lds_dwordx4 v[130:131], off
	s_add_u32 s14, s14, 0xb0080
	s_addc_u32 s15, s15, 0
	s_add_i32 s18, s18, s5
	s_mov_b32 m0, s18
	v_lshl_add_u64 v[130:131], s[14:15], 0, v[128:129]
	global_load_lds_dwordx4 v[130:131], off
	s_add_i32 m0, s18, 0x2000
	v_lshl_add_u64 v[130:131], s[14:15], 0, v[148:149]
	global_load_lds_dwordx4 v[130:131], off
	s_waitcnt vmcnt(8) lgkmcnt(0)
	s_barrier
	v_mfma_f32_16x16x32_bf16 v[60:63], v[154:157], v[176:179], v[60:63]
	v_mfma_f32_16x16x32_bf16 v[56:59], v[168:171], v[176:179], v[56:59]
	v_mfma_f32_16x16x32_bf16 v[44:47], v[154:157], v[184:187], v[44:47]
	v_mfma_f32_16x16x32_bf16 v[40:43], v[168:171], v[184:187], v[40:43]
	v_mfma_f32_16x16x32_bf16 v[28:31], v[154:157], v[192:195], v[28:31]
	v_mfma_f32_16x16x32_bf16 v[24:27], v[168:171], v[192:195], v[24:27]
	v_mfma_f32_16x16x32_bf16 v[12:15], v[154:157], v[200:203], v[12:15]
	v_mfma_f32_16x16x32_bf16 v[8:11], v[168:171], v[200:203], v[8:11]
	v_mfma_f32_16x16x32_bf16 v[60:63], v[164:167], v[180:183], v[60:63]
	v_mfma_f32_16x16x32_bf16 v[56:59], v[172:175], v[180:183], v[56:59]
	v_mfma_f32_16x16x32_bf16 v[44:47], v[164:167], v[188:191], v[44:47]
	v_mfma_f32_16x16x32_bf16 v[40:43], v[172:175], v[188:191], v[40:43]
	v_mfma_f32_16x16x32_bf16 v[28:31], v[164:167], v[196:199], v[28:31]
	v_mfma_f32_16x16x32_bf16 v[24:27], v[172:175], v[196:199], v[24:27]
	v_mfma_f32_16x16x32_bf16 v[12:15], v[164:167], v[204:207], v[12:15]
	v_mfma_f32_16x16x32_bf16 v[8:11], v[172:175], v[204:207], v[8:11]
	v_mfma_f32_16x16x32_bf16 v[52:55], v[208:211], v[176:179], v[52:55]
	v_mfma_f32_16x16x32_bf16 v[48:51], v[216:219], v[176:179], v[48:51]
	v_mfma_f32_16x16x32_bf16 v[36:39], v[208:211], v[184:187], v[36:39]
	v_mfma_f32_16x16x32_bf16 v[32:35], v[216:219], v[184:187], v[32:35]
	v_mfma_f32_16x16x32_bf16 v[20:23], v[208:211], v[192:195], v[20:23]
	v_mfma_f32_16x16x32_bf16 v[16:19], v[216:219], v[192:195], v[16:19]
	v_mfma_f32_16x16x32_bf16 v[4:7], v[208:211], v[200:203], v[4:7]
	v_mfma_f32_16x16x32_bf16 v[0:3], v[216:219], v[200:203], v[0:3]
	v_mfma_f32_16x16x32_bf16 v[52:55], v[212:215], v[180:183], v[52:55]
	v_mfma_f32_16x16x32_bf16 v[48:51], v[220:223], v[180:183], v[48:51]
	v_mfma_f32_16x16x32_bf16 v[36:39], v[212:215], v[188:191], v[36:39]
	v_mfma_f32_16x16x32_bf16 v[32:35], v[220:223], v[188:191], v[32:35]
	v_mfma_f32_16x16x32_bf16 v[20:23], v[212:215], v[196:199], v[20:23]
	v_mfma_f32_16x16x32_bf16 v[16:19], v[220:223], v[196:199], v[16:19]
	v_mfma_f32_16x16x32_bf16 v[4:7], v[212:215], v[204:207], v[4:7]
	v_mfma_f32_16x16x32_bf16 v[0:3], v[220:223], v[204:207], v[0:3]
	s_add_i32 s25, s25, 2
	s_add_u32 s30, s30, 0x100
	s_addc_u32 s31, s31, 0
	s_add_u32 s0, s0, 0x100
	s_addc_u32 s1, s1, 0
	s_cmp_gt_u32 s25, 41
	s_cbranch_scc1 .Lg2_exit
	s_barrier
	s_branch .LBB0_345

.Lg2_epi:
	s_setprio 0
	s_nop 0
	s_nop 0
	s_nop 0
	s_nop 0
	s_nop 0
	s_nop 0
	s_nop 0
	s_nop 0
	s_nop 0
	s_nop 0
	s_nop 0
	s_nop 0
	s_nop 0
	s_nop 0
	s_nop 0
	s_nop 0
	s_cmp_lt_i32 s47, 0
	s_cselect_b64 s[14:15], -1, 0
	s_cmp_gt_i32 s47, -1
	s_cbranch_scc1 .LBB0_348
	v_mul_f32_e32 v131, 0x3d372713, v120
	v_mul_f32_e32 v131, v120, v131
	v_fma_f32 v131, v120, v131, v120
	v_mul_f32_e32 v131, 0x3fcc422a, v131
	v_mul_f32_e32 v131, 0xbfb8aa3b, v131
	v_exp_f32_e32 v131, v131
	v_mul_f32_e32 v130, 0x3d372713, v124
	v_mul_f32_e32 v130, v124, v130
	v_fma_f32 v130, v124, v130, v124
	v_add_f32_e32 v131, 1.0, v131
	v_rcp_f32_e32 v132, v131
	v_mul_f32_e32 v131, 0x3d372713, v125
	v_mul_f32_e32 v131, v125, v131
	v_fma_f32 v131, v125, v131, v125
	v_mul_f32_e32 v130, 0x3fcc422a, v130
	v_mul_f32_e32 v131, 0x3fcc422a, v131
	v_mul_f32_e32 v130, 0xbfb8aa3b, v130
	v_mul_f32_e32 v131, 0xbfb8aa3b, v131
	v_mul_f32_e32 v135, 0x3d372713, v122
	v_exp_f32_e32 v130, v130
	v_exp_f32_e32 v131, v131
	v_mul_f32_e32 v135, v122, v135
	v_fma_f32 v135, v122, v135, v122
	v_mul_f32_e32 v135, 0x3fcc422a, v135
	v_mul_f32_e32 v135, 0xbfb8aa3b, v135
	v_add_f32_e32 v130, 1.0, v130
	v_add_f32_e32 v131, 1.0, v131
	v_exp_f32_e32 v135, v135
	v_rcp_f32_e32 v130, v130
	v_rcp_f32_e32 v131, v131
	v_mul_f32_e32 v133, 0x3d372713, v121
	v_add_f32_e32 v135, 1.0, v135
	v_mul_f32_e32 v134, 0x3d372713, v126
	v_rcp_f32_e32 v136, v135
	v_mul_f32_e32 v135, 0x3d372713, v127
	v_pk_mul_f32 v[124:125], v[124:125], v[130:131]
	v_mul_f32_e32 v130, 0x3d372713, v123
	v_mul_f32_e32 v133, v121, v133
	v_mul_f32_e32 v134, v126, v134
	v_mul_f32_e32 v135, v127, v135
	v_mul_f32_e32 v130, v123, v130
	v_fma_f32 v133, v121, v133, v121
	v_fma_f32 v134, v126, v134, v126
	v_fma_f32 v135, v127, v135, v127
	v_fma_f32 v130, v123, v130, v123
	v_mul_f32_e32 v133, 0x3fcc422a, v133
	v_mul_f32_e32 v134, 0x3fcc422a, v134
	v_mul_f32_e32 v135, 0x3fcc422a, v135
	v_mul_f32_e32 v130, 0x3fcc422a, v130
	v_mul_f32_e32 v133, 0xbfb8aa3b, v133
	v_mul_f32_e32 v134, 0xbfb8aa3b, v134
	v_mul_f32_e32 v135, 0xbfb8aa3b, v135
	v_mul_f32_e32 v130, 0xbfb8aa3b, v130
	v_exp_f32_e32 v133, v133
	v_exp_f32_e32 v134, v134
	v_exp_f32_e32 v135, v135
	v_exp_f32_e32 v130, v130
	v_add_f32_e32 v133, 1.0, v133
	v_add_f32_e32 v134, 1.0, v134
	v_add_f32_e32 v135, 1.0, v135
	v_add_f32_e32 v130, 1.0, v130
	v_rcp_f32_e32 v133, v133
	v_rcp_f32_e32 v134, v134
	v_rcp_f32_e32 v135, v135
	v_rcp_f32_e32 v137, v130
	v_pk_mul_f32 v[120:121], v[120:121], v[132:133]
	v_pk_mul_f32 v[126:127], v[126:127], v[134:135]
	v_pk_mul_f32 v[122:123], v[122:123], v[136:137]

.Lg1_enter:
.LBB0_391:
	s_add_u32 s14, s30, 0xfffc0080
	s_addc_u32 s15, s31, -1
	s_add_i32 s20, 16, 0x10000
	v_add_u32_e32 v130, s20, v156
	ds_read_b128 v[166:169], v130
	ds_read_b128 v[170:173], v130 offset:1024
	ds_read_b128 v[174:177], v130 offset:2048
	ds_read_b128 v[178:181], v130 offset:3072
	s_cmp_eq_u32 s92, 12
	s_cselect_b32 s19, s1, s15
	s_cselect_b32 s18, s13, s14
	s_cselect_b32 s15, s9, s47
	s_cselect_b32 s14, s24, s25
	v_lshl_add_u64 v[130:131], s[30:31], 0, v[150:151]
	s_add_i32 m0, s34, 0xc000
	ds_read_b128 v[182:185], v158
	ds_read_b128 v[186:189], v158 offset:1024
	ds_read_b128 v[190:193], v158 offset:2048
	ds_read_b128 v[194:197], v158 offset:3072
	ds_read_b128 v[198:201], v158 offset:4096
	ds_read_b128 v[202:205], v158 offset:5120
	ds_read_b128 v[206:209], v158 offset:6144
	ds_read_b128 v[210:213], v158 offset:7168
	global_load_lds_dwordx4 v[130:131], off
	s_add_i32 m0, s34, 0xe000
	v_lshl_add_u64 v[130:131], s[30:31], 0, v[152:153]
	global_load_lds_dwordx4 v[130:131], off
	s_add_i32 s50, 16, 0x14000
	v_add_u32_e32 v130, s50, v156
	ds_read_b128 v[214:217], v130
	ds_read_b128 v[218:221], v130 offset:1024
	ds_read_b128 v[222:225], v130 offset:2048
	ds_read_b128 v[226:229], v130 offset:3072
	s_waitcnt vmcnt(8) lgkmcnt(0)
	s_barrier
	v_mfma_f32_16x16x32_bf16 v[116:119], v[166:169], v[182:185], v[116:119]
	v_mfma_f32_16x16x32_bf16 v[112:115], v[174:177], v[182:185], v[112:115]
	v_mfma_f32_16x16x32_bf16 v[100:103], v[166:169], v[190:193], v[100:103]
	v_mfma_f32_16x16x32_bf16 v[96:99], v[174:177], v[190:193], v[96:99]
	v_mfma_f32_16x16x32_bf16 v[84:87], v[166:169], v[198:201], v[84:87]
	v_mfma_f32_16x16x32_bf16 v[80:83], v[174:177], v[198:201], v[80:83]
	v_mfma_f32_16x16x32_bf16 v[68:71], v[166:169], v[206:209], v[68:71]
	v_mfma_f32_16x16x32_bf16 v[64:67], v[174:177], v[206:209], v[64:67]
	v_mfma_f32_16x16x32_bf16 v[116:119], v[170:173], v[186:189], v[116:119]
	v_mfma_f32_16x16x32_bf16 v[112:115], v[178:181], v[186:189], v[112:115]
	v_mfma_f32_16x16x32_bf16 v[100:103], v[170:173], v[194:197], v[100:103]
	v_mfma_f32_16x16x32_bf16 v[96:99], v[178:181], v[194:197], v[96:99]
	v_mfma_f32_16x16x32_bf16 v[84:87], v[170:173], v[202:205], v[84:87]
	v_mfma_f32_16x16x32_bf16 v[80:83], v[178:181], v[202:205], v[80:83]
	v_mfma_f32_16x16x32_bf16 v[68:71], v[170:173], v[210:213], v[68:71]
	v_mfma_f32_16x16x32_bf16 v[64:67], v[178:181], v[210:213], v[64:67]
	v_mfma_f32_16x16x32_bf16 v[124:127], v[214:217], v[182:185], v[124:127]
	v_mfma_f32_16x16x32_bf16 v[120:123], v[222:225], v[182:185], v[120:123]
	v_mfma_f32_16x16x32_bf16 v[108:111], v[214:217], v[190:193], v[108:111]
	v_mfma_f32_16x16x32_bf16 v[104:107], v[222:225], v[190:193], v[104:107]
	v_mfma_f32_16x16x32_bf16 v[92:95], v[214:217], v[198:201], v[92:95]
	v_mfma_f32_16x16x32_bf16 v[88:91], v[222:225], v[198:201], v[88:91]
	v_mfma_f32_16x16x32_bf16 v[76:79], v[214:217], v[206:209], v[76:79]
	v_mfma_f32_16x16x32_bf16 v[72:75], v[222:225], v[206:209], v[72:75]
	v_mfma_f32_16x16x32_bf16 v[124:127], v[218:221], v[186:189], v[124:127]
	v_mfma_f32_16x16x32_bf16 v[120:123], v[226:229], v[186:189], v[120:123]
	v_mfma_f32_16x16x32_bf16 v[108:111], v[218:221], v[194:197], v[108:111]
	v_mfma_f32_16x16x32_bf16 v[104:107], v[226:229], v[194:197], v[104:107]
	v_mfma_f32_16x16x32_bf16 v[92:95], v[218:221], v[202:205], v[92:95]
	v_mfma_f32_16x16x32_bf16 v[88:91], v[226:229], v[202:205], v[88:91]
	v_mfma_f32_16x16x32_bf16 v[76:79], v[218:221], v[210:213], v[76:79]
	v_mfma_f32_16x16x32_bf16 v[72:75], v[226:229], v[210:213], v[72:75]
	s_barrier
	ds_read_b128 v[182:185], v158 offset:16384
	ds_read_b128 v[186:189], v158 offset:17408
	ds_read_b128 v[190:193], v158 offset:18432
	ds_read_b128 v[194:197], v158 offset:19456
	ds_read_b128 v[198:201], v158 offset:20480
	ds_read_b128 v[202:205], v158 offset:21504
	ds_read_b128 v[206:209], v158 offset:22528
	ds_read_b128 v[210:213], v158 offset:23552
	s_add_i32 s20, s20, s5
	v_lshl_add_u64 v[130:131], s[14:15], 0, v[128:129]
	s_mov_b32 m0, s20
	v_lshl_add_u64 v[132:133], s[14:15], 0, v[144:145]
	global_load_lds_dwordx4 v[130:131], off
	s_add_i32 m0, s20, 0x2000
	s_nop 0
	global_load_lds_dwordx4 v[132:133], off
	s_mov_b32 m0, s34
	v_lshl_add_u64 v[134:135], s[18:19], 0, v[148:149]
	global_load_lds_dwordx4 v[134:135], off
	s_mov_b32 m0, s35
	v_lshl_add_u64 v[136:137], s[18:19], 0, v[146:147]
	global_load_lds_dwordx4 v[136:137], off
	s_add_u32 s48, s14, 0x40000
	s_addc_u32 s49, s15, 0
	s_add_i32 s20, s50, s5
	s_mov_b32 m0, s20
	v_lshl_add_u64 v[138:139], s[48:49], 0, v[128:129]
	global_load_lds_dwordx4 v[138:139], off
	s_add_i32 m0, s20, 0x2000
	v_lshl_add_u64 v[138:139], s[48:49], 0, v[144:145]
	global_load_lds_dwordx4 v[138:139], off
	s_waitcnt vmcnt(8) lgkmcnt(0)
	s_barrier
	v_mfma_f32_16x16x32_bf16 v[52:55], v[166:169], v[182:185], v[52:55]
	v_mfma_f32_16x16x32_bf16 v[48:51], v[174:177], v[182:185], v[48:51]
	v_mfma_f32_16x16x32_bf16 v[36:39], v[166:169], v[190:193], v[36:39]
	v_mfma_f32_16x16x32_bf16 v[32:35], v[174:177], v[190:193], v[32:35]
	v_mfma_f32_16x16x32_bf16 v[20:23], v[166:169], v[198:201], v[20:23]
	v_mfma_f32_16x16x32_bf16 v[16:19], v[174:177], v[198:201], v[16:19]
	v_mfma_f32_16x16x32_bf16 v[4:7], v[166:169], v[206:209], v[4:7]
	v_mfma_f32_16x16x32_bf16 v[0:3], v[174:177], v[206:209], v[0:3]
	v_mfma_f32_16x16x32_bf16 v[52:55], v[170:173], v[186:189], v[52:55]
	v_mfma_f32_16x16x32_bf16 v[48:51], v[178:181], v[186:189], v[48:51]
	v_mfma_f32_16x16x32_bf16 v[36:39], v[170:173], v[194:197], v[36:39]
	v_mfma_f32_16x16x32_bf16 v[32:35], v[178:181], v[194:197], v[32:35]
	v_mfma_f32_16x16x32_bf16 v[20:23], v[170:173], v[202:205], v[20:23]
	v_mfma_f32_16x16x32_bf16 v[16:19], v[178:181], v[202:205], v[16:19]
	v_mfma_f32_16x16x32_bf16 v[4:7], v[170:173], v[210:213], v[4:7]
	v_mfma_f32_16x16x32_bf16 v[0:3], v[178:181], v[210:213], v[0:3]
	v_mfma_f32_16x16x32_bf16 v[60:63], v[214:217], v[182:185], v[60:63]
	v_mfma_f32_16x16x32_bf16 v[56:59], v[222:225], v[182:185], v[56:59]
	v_mfma_f32_16x16x32_bf16 v[44:47], v[214:217], v[190:193], v[44:47]
	v_mfma_f32_16x16x32_bf16 v[40:43], v[222:225], v[190:193], v[40:43]
	v_mfma_f32_16x16x32_bf16 v[28:31], v[214:217], v[198:201], v[28:31]
	v_mfma_f32_16x16x32_bf16 v[24:27], v[222:225], v[198:201], v[24:27]
	v_mfma_f32_16x16x32_bf16 v[12:15], v[214:217], v[206:209], v[12:15]
	v_mfma_f32_16x16x32_bf16 v[8:11], v[222:225], v[206:209], v[8:11]
	v_mfma_f32_16x16x32_bf16 v[60:63], v[218:221], v[186:189], v[60:63]
	v_mfma_f32_16x16x32_bf16 v[56:59], v[226:229], v[186:189], v[56:59]
	v_mfma_f32_16x16x32_bf16 v[44:47], v[218:221], v[194:197], v[44:47]
	v_mfma_f32_16x16x32_bf16 v[40:43], v[226:229], v[194:197], v[40:43]
	v_mfma_f32_16x16x32_bf16 v[28:31], v[218:221], v[202:205], v[28:31]
	v_mfma_f32_16x16x32_bf16 v[24:27], v[226:229], v[202:205], v[24:27]
	v_mfma_f32_16x16x32_bf16 v[12:15], v[218:221], v[210:213], v[12:15]
	v_mfma_f32_16x16x32_bf16 v[8:11], v[226:229], v[210:213], v[8:11]
	s_add_i32 s20, 16, 0x18000
	v_add_u32_e32 v138, s20, v156
	s_barrier
	ds_read_b128 v[166:169], v138
	ds_read_b128 v[170:173], v138 offset:1024
	ds_read_b128 v[174:177], v138 offset:2048
	ds_read_b128 v[178:181], v138 offset:3072
	s_add_u32 s18, s18, 0x40000
	s_addc_u32 s19, s19, 0
	s_mov_b32 m0, s36
	v_lshl_add_u64 v[214:215], s[18:19], 0, v[148:149]
	ds_read_b128 v[182:185], v158 offset:32768
	ds_read_b128 v[186:189], v158 offset:33792
	ds_read_b128 v[190:193], v158 offset:34816
	ds_read_b128 v[194:197], v158 offset:35840
	ds_read_b128 v[198:201], v158 offset:36864
	ds_read_b128 v[202:205], v158 offset:37888
	ds_read_b128 v[206:209], v158 offset:38912
	ds_read_b128 v[210:213], v158 offset:39936
	global_load_lds_dwordx4 v[214:215], off
	s_mov_b32 m0, s37
	v_lshl_add_u64 v[214:215], s[18:19], 0, v[146:147]
	global_load_lds_dwordx4 v[214:215], off
	s_add_i32 s18, 16, 0x1c000
	v_add_u32_e32 v138, s18, v156
	ds_read_b128 v[214:217], v138
	ds_read_b128 v[218:221], v138 offset:1024
	ds_read_b128 v[222:225], v138 offset:2048
	ds_read_b128 v[226:229], v138 offset:3072
	s_waitcnt vmcnt(8) lgkmcnt(0)
	s_barrier
	v_mfma_f32_16x16x32_bf16 v[116:119], v[166:169], v[182:185], v[116:119]
	v_mfma_f32_16x16x32_bf16 v[112:115], v[174:177], v[182:185], v[112:115]
	v_mfma_f32_16x16x32_bf16 v[100:103], v[166:169], v[190:193], v[100:103]
	v_mfma_f32_16x16x32_bf16 v[96:99], v[174:177], v[190:193], v[96:99]
	v_mfma_f32_16x16x32_bf16 v[84:87], v[166:169], v[198:201], v[84:87]
	v_mfma_f32_16x16x32_bf16 v[80:83], v[174:177], v[198:201], v[80:83]
	v_mfma_f32_16x16x32_bf16 v[68:71], v[166:169], v[206:209], v[68:71]
	v_mfma_f32_16x16x32_bf16 v[64:67], v[174:177], v[206:209], v[64:67]
	v_mfma_f32_16x16x32_bf16 v[116:119], v[170:173], v[186:189], v[116:119]
	v_mfma_f32_16x16x32_bf16 v[112:115], v[178:181], v[186:189], v[112:115]
	v_mfma_f32_16x16x32_bf16 v[100:103], v[170:173], v[194:197], v[100:103]
	v_mfma_f32_16x16x32_bf16 v[96:99], v[178:181], v[194:197], v[96:99]
	v_mfma_f32_16x16x32_bf16 v[84:87], v[170:173], v[202:205], v[84:87]
	v_mfma_f32_16x16x32_bf16 v[80:83], v[178:181], v[202:205], v[80:83]
	v_mfma_f32_16x16x32_bf16 v[68:71], v[170:173], v[210:213], v[68:71]
	v_mfma_f32_16x16x32_bf16 v[64:67], v[178:181], v[210:213], v[64:67]
	v_mfma_f32_16x16x32_bf16 v[124:127], v[214:217], v[182:185], v[124:127]
	v_mfma_f32_16x16x32_bf16 v[120:123], v[222:225], v[182:185], v[120:123]
	v_mfma_f32_16x16x32_bf16 v[108:111], v[214:217], v[190:193], v[108:111]
	v_mfma_f32_16x16x32_bf16 v[104:107], v[222:225], v[190:193], v[104:107]
	v_mfma_f32_16x16x32_bf16 v[92:95], v[214:217], v[198:201], v[92:95]
	v_mfma_f32_16x16x32_bf16 v[88:91], v[222:225], v[198:201], v[88:91]
	v_mfma_f32_16x16x32_bf16 v[76:79], v[214:217], v[206:209], v[76:79]
	v_mfma_f32_16x16x32_bf16 v[72:75], v[222:225], v[206:209], v[72:75]
	v_mfma_f32_16x16x32_bf16 v[124:127], v[218:221], v[186:189], v[124:127]
	v_mfma_f32_16x16x32_bf16 v[120:123], v[226:229], v[186:189], v[120:123]
	v_mfma_f32_16x16x32_bf16 v[108:111], v[218:221], v[194:197], v[108:111]
	v_mfma_f32_16x16x32_bf16 v[104:107], v[226:229], v[194:197], v[104:107]
	v_mfma_f32_16x16x32_bf16 v[92:95], v[218:221], v[202:205], v[92:95]
	v_mfma_f32_16x16x32_bf16 v[88:91], v[226:229], v[202:205], v[88:91]
	v_mfma_f32_16x16x32_bf16 v[76:79], v[218:221], v[210:213], v[76:79]
	v_mfma_f32_16x16x32_bf16 v[72:75], v[226:229], v[210:213], v[72:75]
	s_barrier
	ds_read_b128 v[182:185], v158 offset:49152
	ds_read_b128 v[186:189], v158 offset:50176
	ds_read_b128 v[190:193], v158 offset:51200
	ds_read_b128 v[194:197], v158 offset:52224
	ds_read_b128 v[198:201], v158 offset:53248
	ds_read_b128 v[202:205], v158 offset:54272
	ds_read_b128 v[206:209], v158 offset:55296
	ds_read_b128 v[210:213], v158 offset:56320
	s_add_i32 s19, s20, s5
	s_mov_b32 m0, s19
	v_lshl_add_u64 v[130:131], v[130:131], 0, s[28:29]
	global_load_lds_dwordx4 v[130:131], off
	s_add_i32 m0, s19, 0x2000
	v_lshl_add_u64 v[130:131], v[132:133], 0, s[28:29]
	global_load_lds_dwordx4 v[130:131], off
	s_mov_b32 m0, s44
	v_lshl_add_u64 v[130:131], v[134:135], 0, s[28:29]
	global_load_lds_dwordx4 v[130:131], off
	s_mov_b32 m0, s45
	v_lshl_add_u64 v[130:131], v[136:137], 0, s[28:29]
	global_load_lds_dwordx4 v[130:131], off
	s_add_u32 s14, s14, 0x40080
	s_addc_u32 s15, s15, 0
	s_add_i32 s18, s18, s5
	s_mov_b32 m0, s18
	v_lshl_add_u64 v[130:131], s[14:15], 0, v[128:129]
	global_load_lds_dwordx4 v[130:131], off
	s_add_i32 m0, s18, 0x2000
	v_lshl_add_u64 v[130:131], s[14:15], 0, v[144:145]
	global_load_lds_dwordx4 v[130:131], off
	s_waitcnt vmcnt(8) lgkmcnt(0)
	s_barrier
	v_mfma_f32_16x16x32_bf16 v[52:55], v[166:169], v[182:185], v[52:55]
	v_mfma_f32_16x16x32_bf16 v[48:51], v[174:177], v[182:185], v[48:51]
	v_mfma_f32_16x16x32_bf16 v[36:39], v[166:169], v[190:193], v[36:39]
	v_mfma_f32_16x16x32_bf16 v[32:35], v[174:177], v[190:193], v[32:35]
	v_mfma_f32_16x16x32_bf16 v[20:23], v[166:169], v[198:201], v[20:23]
	v_mfma_f32_16x16x32_bf16 v[16:19], v[174:177], v[198:201], v[16:19]
	v_mfma_f32_16x16x32_bf16 v[4:7], v[166:169], v[206:209], v[4:7]
	v_mfma_f32_16x16x32_bf16 v[0:3], v[174:177], v[206:209], v[0:3]
	v_mfma_f32_16x16x32_bf16 v[52:55], v[170:173], v[186:189], v[52:55]
	v_mfma_f32_16x16x32_bf16 v[48:51], v[178:181], v[186:189], v[48:51]
	v_mfma_f32_16x16x32_bf16 v[36:39], v[170:173], v[194:197], v[36:39]
	v_mfma_f32_16x16x32_bf16 v[32:35], v[178:181], v[194:197], v[32:35]
	v_mfma_f32_16x16x32_bf16 v[20:23], v[170:173], v[202:205], v[20:23]
	v_mfma_f32_16x16x32_bf16 v[16:19], v[178:181], v[202:205], v[16:19]
	v_mfma_f32_16x16x32_bf16 v[4:7], v[170:173], v[210:213], v[4:7]
	v_mfma_f32_16x16x32_bf16 v[0:3], v[178:181], v[210:213], v[0:3]
	v_mfma_f32_16x16x32_bf16 v[60:63], v[214:217], v[182:185], v[60:63]
	v_mfma_f32_16x16x32_bf16 v[56:59], v[222:225], v[182:185], v[56:59]
	v_mfma_f32_16x16x32_bf16 v[44:47], v[214:217], v[190:193], v[44:47]
	v_mfma_f32_16x16x32_bf16 v[40:43], v[222:225], v[190:193], v[40:43]
	v_mfma_f32_16x16x32_bf16 v[28:31], v[214:217], v[198:201], v[28:31]
	v_mfma_f32_16x16x32_bf16 v[24:27], v[222:225], v[198:201], v[24:27]
	v_mfma_f32_16x16x32_bf16 v[12:15], v[214:217], v[206:209], v[12:15]
	v_mfma_f32_16x16x32_bf16 v[8:11], v[222:225], v[206:209], v[8:11]
	v_mfma_f32_16x16x32_bf16 v[60:63], v[218:221], v[186:189], v[60:63]
	v_mfma_f32_16x16x32_bf16 v[56:59], v[226:229], v[186:189], v[56:59]
	v_mfma_f32_16x16x32_bf16 v[44:47], v[218:221], v[194:197], v[44:47]
	v_mfma_f32_16x16x32_bf16 v[40:43], v[226:229], v[194:197], v[40:43]
	v_mfma_f32_16x16x32_bf16 v[28:31], v[218:221], v[202:205], v[28:31]
	v_mfma_f32_16x16x32_bf16 v[24:27], v[226:229], v[202:205], v[24:27]
	v_mfma_f32_16x16x32_bf16 v[12:15], v[218:221], v[210:213], v[12:15]
	v_mfma_f32_16x16x32_bf16 v[8:11], v[226:229], v[210:213], v[8:11]
	s_add_i32 s92, s92, 2
	s_add_u32 s30, s30, 0x100
	s_addc_u32 s31, s31, 0
	s_add_u32 s25, s25, 0x100
	s_addc_u32 s47, s47, 0
	s_cmp_gt_u32 s92, 13
	s_cbranch_scc1 .Lg1_exit
	s_barrier
	s_branch .LBB0_391

.Lg1_epi:
	s_setprio 0
	s_nop 0
	s_nop 0
	s_nop 0
	s_nop 0
	s_nop 0
	s_nop 0
	s_nop 0
	s_nop 0
	s_nop 0
	s_nop 0
	s_nop 0
	s_nop 0
	s_nop 0
	s_nop 0
	s_nop 0
	s_nop 0
	s_waitcnt vmcnt(0)
	v_fmamk_f32 v132, v165, 0x3a800000, v235
	v_cmp_gt_f32_e32 vcc, s86, v132
	v_mul_f32_e32 v133, 0x4b800000, v132
	v_pk_mul_f32 v[126:127], v[118:119], v[126:127]
	v_cndmask_b32_e32 v132, v132, v133, vcc
	v_rsq_f32_e32 v132, v132
	v_pk_mul_f32 v[122:123], v[114:115], v[122:123]
	v_lshl_or_b32 v130, s0, 7, v157
	v_ashrrev_i32_e32 v131, 31, v130
	v_mul_f32_e32 v133, 0x45800000, v132
	v_cndmask_b32_e32 v132, v132, v133, vcc
	v_mul_f32_e32 v133, 0xbfb8aa3b, v132
	v_mul_f32_e32 v135, v133, v112
	v_exp_f32_e32 v135, v135
	v_mul_f32_e32 v134, v133, v116
	v_exp_f32_e32 v134, v134
	v_mul_f32_e32 v132, v132, v132
	v_add_f32_e32 v135, 1.0, v135
	v_rcp_f32_e32 v136, v135
	v_mul_f32_e32 v135, v133, v117
	v_exp_f32_e32 v135, v135
	v_add_f32_e32 v134, 1.0, v134
	v_rcp_f32_e32 v134, v134
	v_pk_mul_f32 v[116:117], v[116:117], v[124:125]
	v_add_f32_e32 v135, 1.0, v135
	v_rcp_f32_e32 v135, v135
	v_mul_f32_e32 v118, v133, v118
	v_mul_f32_e32 v119, v133, v119
	v_exp_f32_e32 v118, v118
	v_pk_mul_f32 v[124:125], v[132:133], v[134:135] op_sel_hi:[0,1]
	v_pk_mul_f32 v[116:117], v[124:125], v[116:117]
	v_mul_f32_e32 v124, v133, v113
	v_exp_f32_e32 v124, v124
	v_mul_f32_e32 v114, v133, v114
	v_exp_f32_e32 v119, v119
	v_mul_f32_e32 v115, v133, v115
	v_exp_f32_e32 v114, v114
	v_exp_f32_e32 v115, v115
	v_add_f32_e32 v124, 1.0, v124
	v_add_f32_e32 v118, 1.0, v118
	v_add_f32_e32 v119, 1.0, v119
	v_rcp_f32_e32 v137, v124
	v_rcp_f32_e32 v118, v118
	v_add_f32_e32 v114, 1.0, v114
	v_rcp_f32_e32 v119, v119
	v_add_f32_e32 v115, 1.0, v115
	v_rcp_f32_e32 v114, v114
	v_rcp_f32_e32 v115, v115
	v_pk_mul_f32 v[112:113], v[112:113], v[120:121]
	v_pk_mul_f32 v[120:121], v[132:133], v[136:137] op_sel_hi:[0,1]
	v_pk_mul_f32 v[118:119], v[132:133], v[118:119] op_sel_hi:[0,1]
	v_pk_mul_f32 v[112:113], v[120:121], v[112:113]
	v_pk_mul_f32 v[118:119], v[118:119], v[126:127]
	v_pk_mul_f32 v[114:115], v[132:133], v[114:115] op_sel_hi:[0,1]
	v_pk_mul_f32 v[114:115], v[114:115], v[122:123]
	v_cvt_pk_bf16_f32 v116, v116, v117
	v_cvt_pk_bf16_f32 v117, v118, v119
	v_cvt_pk_bf16_f32 v118, v112, v113
	v_mov_b64_e32 v[112:113], s[94:95]
	s_movk_i32 s9, 0x1600
	v_cvt_pk_bf16_f32 v119, v114, v115
	v_mad_i64_i32 v[120:121], s[0:1], v154, s9, v[112:113]
	v_lshlrev_b64 v[114:115], 1, v[130:131]
	v_lshl_add_u64 v[120:121], v[120:121], 0, v[114:115]
	global_store_dwordx4 v[120:121], v[116:119], off nt
	v_pk_mul_f32 v[106:107], v[98:99], v[106:107]
	v_pk_mul_f32 v[110:111], v[102:103], v[110:111]
	v_fmamk_f32 v116, v164, 0x3a800000, v235
	v_cmp_gt_f32_e32 vcc, s86, v116
	v_mul_f32_e32 v117, 0x4b800000, v116
	v_pk_mul_f32 v[90:91], v[82:83], v[90:91]
	v_cndmask_b32_e32 v116, v116, v117, vcc
	v_rsq_f32_e32 v116, v116
	v_pk_mul_f32 v[94:95], v[86:87], v[94:95]
	v_pk_mul_f32 v[74:75], v[66:67], v[74:75]
	v_pk_mul_f32 v[78:79], v[70:71], v[78:79]
	v_mul_f32_e32 v117, 0x45800000, v116
	v_cndmask_b32_e32 v116, v116, v117, vcc
	v_mul_f32_e32 v117, 0xbfb8aa3b, v116
	v_mul_f32_e32 v119, v117, v96
	v_exp_f32_e32 v119, v119
	v_mul_f32_e32 v118, v117, v100
	v_exp_f32_e32 v118, v118
	v_mul_f32_e32 v116, v116, v116
	v_add_f32_e32 v119, 1.0, v119
	v_rcp_f32_e32 v120, v119
	v_mul_f32_e32 v119, v117, v101
	v_exp_f32_e32 v119, v119
	v_add_f32_e32 v118, 1.0, v118
	v_rcp_f32_e32 v118, v118
	v_pk_mul_f32 v[100:101], v[100:101], v[108:109]
	v_add_f32_e32 v119, 1.0, v119
	v_rcp_f32_e32 v119, v119
	v_pk_mul_f32 v[58:59], v[50:51], v[58:59]
	v_pk_mul_f32 v[62:63], v[54:55], v[62:63]
	v_pk_mul_f32 v[42:43], v[34:35], v[42:43]
	v_pk_mul_f32 v[108:109], v[116:117], v[118:119] op_sel_hi:[0,1]
	v_pk_mul_f32 v[100:101], v[108:109], v[100:101]
	v_mul_f32_e32 v108, v117, v97
	v_exp_f32_e32 v108, v108
	v_pk_mul_f32 v[96:97], v[96:97], v[104:105]
	v_pk_mul_f32 v[46:47], v[38:39], v[46:47]
	v_pk_mul_f32 v[26:27], v[18:19], v[26:27]
	v_add_f32_e32 v108, 1.0, v108
	v_rcp_f32_e32 v121, v108
	v_or_b32_e32 v108, 16, v154
	v_pk_mul_f32 v[30:31], v[22:23], v[30:31]
	v_pk_mul_f32 v[10:11], v[2:3], v[10:11]
	v_pk_mul_f32 v[104:105], v[116:117], v[120:121] op_sel_hi:[0,1]
	v_pk_mul_f32 v[104:105], v[104:105], v[96:97]
	v_mul_f32_e32 v97, v117, v98
	v_exp_f32_e32 v97, v97
	v_mul_f32_e32 v96, v117, v102
	v_exp_f32_e32 v96, v96
	v_pk_mul_f32 v[14:15], v[6:7], v[14:15]
	v_add_f32_e32 v97, 1.0, v97
	v_rcp_f32_e32 v98, v97
	v_mul_f32_e32 v97, v117, v103
	v_exp_f32_e32 v97, v97
	v_add_f32_e32 v96, 1.0, v96
	v_rcp_f32_e32 v96, v96
	s_mov_b32 s20, s12
	v_add_f32_e32 v97, 1.0, v97
	v_rcp_f32_e32 v97, v97
	s_mov_b64 s[14:15], s[42:43]
	s_mov_b64 s[18:19], s[40:41]
	v_pk_mul_f32 v[96:97], v[116:117], v[96:97] op_sel_hi:[0,1]
	v_pk_mul_f32 v[102:103], v[96:97], v[110:111]
	v_mul_f32_e32 v96, v117, v99
	v_exp_f32_e32 v96, v96
	s_nop 0
	v_add_f32_e32 v96, 1.0, v96
	v_rcp_f32_e32 v99, v96
	s_nop 0
	v_pk_mul_f32 v[96:97], v[116:117], v[98:99] op_sel_hi:[0,1]
	v_pk_mul_f32 v[106:107], v[96:97], v[106:107]
	v_cvt_pk_bf16_f32 v96, v100, v101
	v_mad_i64_i32 v[100:101], s[0:1], v108, s9, v[112:113]
	v_cvt_pk_bf16_f32 v97, v102, v103
	v_cvt_pk_bf16_f32 v98, v104, v105
	v_cvt_pk_bf16_f32 v99, v106, v107
	v_lshl_add_u64 v[100:101], v[100:101], 0, v[114:115]
	global_store_dwordx4 v[100:101], v[96:99], off nt
	s_nop 1
	v_fmamk_f32 v96, v163, 0x3a800000, v235
	v_cmp_gt_f32_e32 vcc, s86, v96
	v_mul_f32_e32 v97, 0x4b800000, v96
	s_nop 0
	v_cndmask_b32_e32 v96, v96, v97, vcc
	v_rsq_f32_e32 v96, v96
	s_nop 0
	v_mul_f32_e32 v97, 0x45800000, v96
	v_cndmask_b32_e32 v96, v96, v97, vcc
	v_mul_f32_e32 v97, 0xbfb8aa3b, v96
	v_mul_f32_e32 v99, v97, v80
	v_exp_f32_e32 v99, v99
	v_mul_f32_e32 v98, v97, v84
	v_exp_f32_e32 v98, v98
	v_mul_f32_e32 v96, v96, v96
	v_add_f32_e32 v99, 1.0, v99
	v_rcp_f32_e32 v100, v99
	v_mul_f32_e32 v99, v97, v85
	v_exp_f32_e32 v99, v99
	v_add_f32_e32 v98, 1.0, v98
	v_rcp_f32_e32 v98, v98
	v_pk_mul_f32 v[84:85], v[84:85], v[92:93]
	v_add_f32_e32 v99, 1.0, v99
	v_rcp_f32_e32 v99, v99
	s_nop 0
	v_pk_mul_f32 v[92:93], v[96:97], v[98:99] op_sel_hi:[0,1]
	v_pk_mul_f32 v[84:85], v[92:93], v[84:85]
	v_mul_f32_e32 v92, v97, v81
	v_exp_f32_e32 v92, v92
	v_pk_mul_f32 v[80:81], v[80:81], v[88:89]
	v_add_f32_e32 v92, 1.0, v92
	v_rcp_f32_e32 v101, v92
	v_or_b32_e32 v92, 32, v154
	v_pk_mul_f32 v[88:89], v[96:97], v[100:101] op_sel_hi:[0,1]
	v_pk_mul_f32 v[88:89], v[88:89], v[80:81]
	v_mul_f32_e32 v81, v97, v82
	v_exp_f32_e32 v81, v81
	v_mul_f32_e32 v80, v97, v86
	v_exp_f32_e32 v80, v80
	v_add_f32_e32 v81, 1.0, v81
	v_rcp_f32_e32 v82, v81
	v_mul_f32_e32 v81, v97, v87
	v_exp_f32_e32 v81, v81
	v_add_f32_e32 v80, 1.0, v80
	v_rcp_f32_e32 v80, v80
	v_add_f32_e32 v81, 1.0, v81
	v_rcp_f32_e32 v81, v81
	s_nop 0
	v_pk_mul_f32 v[80:81], v[96:97], v[80:81] op_sel_hi:[0,1]
	v_pk_mul_f32 v[86:87], v[80:81], v[94:95]
	v_mul_f32_e32 v80, v97, v83
	v_exp_f32_e32 v80, v80
	s_nop 0
	v_add_f32_e32 v80, 1.0, v80
	v_rcp_f32_e32 v83, v80
	s_nop 0
	v_pk_mul_f32 v[80:81], v[96:97], v[82:83] op_sel_hi:[0,1]
	v_pk_mul_f32 v[90:91], v[80:81], v[90:91]
	v_cvt_pk_bf16_f32 v80, v84, v85
	v_mad_i64_i32 v[84:85], s[0:1], v92, s9, v[112:113]
	v_cvt_pk_bf16_f32 v81, v86, v87
	v_cvt_pk_bf16_f32 v82, v88, v89
	v_cvt_pk_bf16_f32 v83, v90, v91
	v_lshl_add_u64 v[84:85], v[84:85], 0, v[114:115]
	global_store_dwordx4 v[84:85], v[80:83], off nt
	s_nop 1
	v_fmamk_f32 v80, v162, 0x3a800000, v235
	v_cmp_gt_f32_e32 vcc, s86, v80
	v_mul_f32_e32 v81, 0x4b800000, v80
	s_nop 0
	v_cndmask_b32_e32 v80, v80, v81, vcc
	v_rsq_f32_e32 v80, v80
	s_nop 0
	v_mul_f32_e32 v81, 0x45800000, v80
	v_cndmask_b32_e32 v80, v80, v81, vcc
	v_mul_f32_e32 v81, 0xbfb8aa3b, v80
	v_mul_f32_e32 v83, v81, v64
	v_exp_f32_e32 v83, v83
	v_mul_f32_e32 v82, v81, v68
	v_exp_f32_e32 v82, v82
	v_mul_f32_e32 v80, v80, v80
	v_add_f32_e32 v83, 1.0, v83
	v_rcp_f32_e32 v84, v83
	v_mul_f32_e32 v83, v81, v69
	v_exp_f32_e32 v83, v83
	v_add_f32_e32 v82, 1.0, v82
	v_rcp_f32_e32 v82, v82
	v_pk_mul_f32 v[68:69], v[68:69], v[76:77]
	v_add_f32_e32 v83, 1.0, v83
	v_rcp_f32_e32 v83, v83
	s_nop 0
	v_pk_mul_f32 v[76:77], v[80:81], v[82:83] op_sel_hi:[0,1]
	v_pk_mul_f32 v[68:69], v[76:77], v[68:69]
	v_mul_f32_e32 v76, v81, v65
	v_exp_f32_e32 v76, v76
	v_pk_mul_f32 v[64:65], v[64:65], v[72:73]
	v_add_f32_e32 v76, 1.0, v76
	v_rcp_f32_e32 v85, v76
	v_or_b32_e32 v76, 48, v154
	v_pk_mul_f32 v[72:73], v[80:81], v[84:85] op_sel_hi:[0,1]
	v_pk_mul_f32 v[72:73], v[72:73], v[64:65]
	v_mul_f32_e32 v65, v81, v66
	v_exp_f32_e32 v65, v65
	v_mul_f32_e32 v64, v81, v70
	v_exp_f32_e32 v64, v64
	v_add_f32_e32 v65, 1.0, v65
	v_rcp_f32_e32 v66, v65
	v_mul_f32_e32 v65, v81, v71
	v_exp_f32_e32 v65, v65
	v_add_f32_e32 v64, 1.0, v64
	v_rcp_f32_e32 v64, v64
	v_add_f32_e32 v65, 1.0, v65
	v_rcp_f32_e32 v65, v65
	s_nop 0
	v_pk_mul_f32 v[64:65], v[80:81], v[64:65] op_sel_hi:[0,1]
	v_pk_mul_f32 v[70:71], v[64:65], v[78:79]
	v_mul_f32_e32 v64, v81, v67
	v_exp_f32_e32 v64, v64
	s_nop 0
	v_add_f32_e32 v64, 1.0, v64
	v_rcp_f32_e32 v67, v64
	s_nop 0
	v_pk_mul_f32 v[64:65], v[80:81], v[66:67] op_sel_hi:[0,1]
	v_pk_mul_f32 v[74:75], v[64:65], v[74:75]
	v_cvt_pk_bf16_f32 v64, v68, v69
	v_mad_i64_i32 v[68:69], s[0:1], v76, s9, v[112:113]
	v_cvt_pk_bf16_f32 v65, v70, v71
	v_cvt_pk_bf16_f32 v66, v72, v73
	v_cvt_pk_bf16_f32 v67, v74, v75
	v_lshl_add_u64 v[68:69], v[68:69], 0, v[114:115]
	global_store_dwordx4 v[68:69], v[64:67], off nt
	s_nop 1
	v_fmamk_f32 v64, v161, 0x3a800000, v235
	v_cmp_gt_f32_e32 vcc, s86, v64
	v_mul_f32_e32 v66, 0x4b800000, v64
	v_add_u32_e32 v65, 0x80, v154
	v_cndmask_b32_e32 v64, v64, v66, vcc
	v_rsq_f32_e32 v64, v64
	s_nop 0
	v_mul_f32_e32 v66, 0x45800000, v64
	v_cndmask_b32_e32 v64, v64, v66, vcc
	v_mul_f32_e32 v70, 0xbfb8aa3b, v64
	v_mul_f32_e32 v67, v70, v48
	v_exp_f32_e32 v67, v67
	v_mul_f32_e32 v66, v70, v52
	v_exp_f32_e32 v66, v66
	v_mul_f32_e32 v64, v64, v64
	v_add_f32_e32 v67, 1.0, v67
	v_rcp_f32_e32 v68, v67
	v_mul_f32_e32 v67, v70, v53
	v_exp_f32_e32 v67, v67
	v_add_f32_e32 v66, 1.0, v66
	v_rcp_f32_e32 v66, v66
	v_pk_mul_f32 v[52:53], v[52:53], v[60:61]
	v_add_f32_e32 v67, 1.0, v67
	v_rcp_f32_e32 v67, v67
	s_nop 0
	v_pk_mul_f32 v[60:61], v[64:65], v[66:67] op_sel_hi:[0,1]
	v_pk_mul_f32 v[52:53], v[60:61], v[52:53]
	v_mul_f32_e32 v60, v70, v49
	v_exp_f32_e32 v60, v60
	v_pk_mul_f32 v[48:49], v[48:49], v[56:57]
	v_add_f32_e32 v60, 1.0, v60
	v_rcp_f32_e32 v69, v60
	s_nop 0
	v_pk_mul_f32 v[56:57], v[64:65], v[68:69] op_sel_hi:[0,1]
	v_pk_mul_f32 v[56:57], v[56:57], v[48:49]
	v_mul_f32_e32 v49, v70, v50
	v_exp_f32_e32 v49, v49
	v_mul_f32_e32 v48, v70, v54
	v_exp_f32_e32 v48, v48
	v_add_f32_e32 v49, 1.0, v49
	v_rcp_f32_e32 v50, v49
	v_mul_f32_e32 v49, v70, v55
	v_exp_f32_e32 v49, v49
	v_add_f32_e32 v48, 1.0, v48
	v_rcp_f32_e32 v48, v48
	v_add_f32_e32 v49, 1.0, v49
	v_rcp_f32_e32 v49, v49
	s_nop 0
	v_pk_mul_f32 v[48:49], v[64:65], v[48:49] op_sel_hi:[0,1]
	v_pk_mul_f32 v[54:55], v[48:49], v[62:63]
	v_mul_f32_e32 v48, v70, v51
	v_exp_f32_e32 v48, v48
	s_nop 0
	v_add_f32_e32 v48, 1.0, v48
	v_rcp_f32_e32 v51, v48
	s_nop 0
	v_pk_mul_f32 v[48:49], v[64:65], v[50:51] op_sel_hi:[0,1]
	v_pk_mul_f32 v[58:59], v[48:49], v[58:59]
	v_cvt_pk_bf16_f32 v48, v52, v53
	v_mad_i64_i32 v[52:53], s[0:1], v65, s9, v[112:113]
	v_cvt_pk_bf16_f32 v49, v54, v55
	v_cvt_pk_bf16_f32 v50, v56, v57
	v_cvt_pk_bf16_f32 v51, v58, v59
	v_lshl_add_u64 v[52:53], v[52:53], 0, v[114:115]
	global_store_dwordx4 v[52:53], v[48:51], off nt
	s_nop 1
	v_fmamk_f32 v48, v160, 0x3a800000, v235
	v_cmp_gt_f32_e32 vcc, s86, v48
	v_mul_f32_e32 v49, 0x4b800000, v48
	s_nop 0
	v_cndmask_b32_e32 v48, v48, v49, vcc
	v_rsq_f32_e32 v48, v48
	s_nop 0
	v_mul_f32_e32 v49, 0x45800000, v48
	v_cndmask_b32_e32 v48, v48, v49, vcc
	v_mul_f32_e32 v49, 0xbfb8aa3b, v48
	v_mul_f32_e32 v51, v49, v32
	v_exp_f32_e32 v51, v51
	v_mul_f32_e32 v50, v49, v36
	v_exp_f32_e32 v50, v50
	v_mul_f32_e32 v48, v48, v48
	v_add_f32_e32 v51, 1.0, v51
	v_rcp_f32_e32 v52, v51
	v_mul_f32_e32 v51, v49, v37
	v_exp_f32_e32 v51, v51
	v_add_f32_e32 v50, 1.0, v50
	v_rcp_f32_e32 v50, v50
	v_pk_mul_f32 v[36:37], v[36:37], v[44:45]
	v_add_f32_e32 v51, 1.0, v51
	v_rcp_f32_e32 v51, v51
	s_nop 0
	v_pk_mul_f32 v[44:45], v[48:49], v[50:51] op_sel_hi:[0,1]
	v_pk_mul_f32 v[36:37], v[44:45], v[36:37]
	v_mul_f32_e32 v44, v49, v33
	v_exp_f32_e32 v44, v44
	v_pk_mul_f32 v[32:33], v[32:33], v[40:41]
	v_add_f32_e32 v44, 1.0, v44
	v_rcp_f32_e32 v53, v44
	v_add_u32_e32 v44, 0x90, v154
	v_pk_mul_f32 v[40:41], v[48:49], v[52:53] op_sel_hi:[0,1]
	v_pk_mul_f32 v[40:41], v[40:41], v[32:33]
	v_mul_f32_e32 v33, v49, v34
	v_exp_f32_e32 v33, v33
	v_mul_f32_e32 v32, v49, v38
	v_exp_f32_e32 v32, v32
	v_add_f32_e32 v33, 1.0, v33
	v_rcp_f32_e32 v34, v33
	v_mul_f32_e32 v33, v49, v39
	v_exp_f32_e32 v33, v33
	v_add_f32_e32 v32, 1.0, v32
	v_rcp_f32_e32 v32, v32
	v_add_f32_e32 v33, 1.0, v33
	v_rcp_f32_e32 v33, v33
	s_nop 0
	v_pk_mul_f32 v[32:33], v[48:49], v[32:33] op_sel_hi:[0,1]
	v_pk_mul_f32 v[38:39], v[32:33], v[46:47]
	v_mul_f32_e32 v32, v49, v35
	v_exp_f32_e32 v32, v32
	s_nop 0
	v_add_f32_e32 v32, 1.0, v32
	v_rcp_f32_e32 v35, v32
	s_nop 0
	v_pk_mul_f32 v[32:33], v[48:49], v[34:35] op_sel_hi:[0,1]
	v_pk_mul_f32 v[42:43], v[32:33], v[42:43]
	v_cvt_pk_bf16_f32 v32, v36, v37
	v_mad_i64_i32 v[36:37], s[0:1], v44, s9, v[112:113]
	v_cvt_pk_bf16_f32 v33, v38, v39
	v_cvt_pk_bf16_f32 v34, v40, v41
	v_cvt_pk_bf16_f32 v35, v42, v43
	v_lshl_add_u64 v[36:37], v[36:37], 0, v[114:115]
	global_store_dwordx4 v[36:37], v[32:35], off nt
	s_nop 1
	v_fmamk_f32 v32, v159, 0x3a800000, v235
	v_cmp_gt_f32_e32 vcc, s86, v32
	v_mul_f32_e32 v33, 0x4b800000, v32
	s_nop 0
	v_cndmask_b32_e32 v32, v32, v33, vcc
	v_rsq_f32_e32 v32, v32
	s_nop 0
	v_mul_f32_e32 v33, 0x45800000, v32
	v_cndmask_b32_e32 v32, v32, v33, vcc
	v_mul_f32_e32 v33, 0xbfb8aa3b, v32
	v_mul_f32_e32 v35, v33, v16
	v_exp_f32_e32 v35, v35
	v_mul_f32_e32 v34, v33, v20
	v_exp_f32_e32 v34, v34
	v_mul_f32_e32 v32, v32, v32
	v_add_f32_e32 v35, 1.0, v35
	v_rcp_f32_e32 v36, v35
	v_mul_f32_e32 v35, v33, v21
	v_exp_f32_e32 v35, v35
	v_add_f32_e32 v34, 1.0, v34
	v_rcp_f32_e32 v34, v34
	v_pk_mul_f32 v[20:21], v[20:21], v[28:29]
	v_add_f32_e32 v35, 1.0, v35
	v_rcp_f32_e32 v35, v35
	s_nop 0
	v_pk_mul_f32 v[28:29], v[32:33], v[34:35] op_sel_hi:[0,1]
	v_pk_mul_f32 v[20:21], v[28:29], v[20:21]
	v_mul_f32_e32 v28, v33, v17
	v_exp_f32_e32 v28, v28
	v_pk_mul_f32 v[16:17], v[16:17], v[24:25]
	v_add_f32_e32 v28, 1.0, v28
	v_rcp_f32_e32 v37, v28
	v_add_u32_e32 v28, 0xa0, v154
	v_pk_mul_f32 v[24:25], v[32:33], v[36:37] op_sel_hi:[0,1]
	v_pk_mul_f32 v[24:25], v[24:25], v[16:17]
	v_mul_f32_e32 v17, v33, v18
	v_exp_f32_e32 v17, v17
	v_mul_f32_e32 v16, v33, v22
	v_exp_f32_e32 v16, v16
	v_add_f32_e32 v17, 1.0, v17
	v_rcp_f32_e32 v18, v17
	v_mul_f32_e32 v17, v33, v23
	v_exp_f32_e32 v17, v17
	v_add_f32_e32 v16, 1.0, v16
	v_rcp_f32_e32 v16, v16
	v_add_f32_e32 v17, 1.0, v17
	v_rcp_f32_e32 v17, v17
	s_nop 0
	v_pk_mul_f32 v[16:17], v[32:33], v[16:17] op_sel_hi:[0,1]
	v_pk_mul_f32 v[22:23], v[16:17], v[30:31]
	v_mul_f32_e32 v16, v33, v19
	v_exp_f32_e32 v16, v16
	s_nop 0
	v_add_f32_e32 v16, 1.0, v16
	v_rcp_f32_e32 v19, v16
	s_nop 0
	v_pk_mul_f32 v[16:17], v[32:33], v[18:19] op_sel_hi:[0,1]
	v_pk_mul_f32 v[26:27], v[16:17], v[26:27]
	v_cvt_pk_bf16_f32 v16, v20, v21
	v_mad_i64_i32 v[20:21], s[0:1], v28, s9, v[112:113]
	v_cvt_pk_bf16_f32 v17, v22, v23
	v_cvt_pk_bf16_f32 v18, v24, v25
	v_cvt_pk_bf16_f32 v19, v26, v27
	v_lshl_add_u64 v[20:21], v[20:21], 0, v[114:115]
	global_store_dwordx4 v[20:21], v[16:19], off nt
	s_nop 1
	v_fmamk_f32 v16, v155, 0x3a800000, v235
	v_cmp_gt_f32_e32 vcc, s86, v16
	v_mul_f32_e32 v17, 0x4b800000, v16
	s_nop 0
	v_cndmask_b32_e32 v16, v16, v17, vcc
	v_rsq_f32_e32 v16, v16
	s_nop 0
	v_mul_f32_e32 v17, 0x45800000, v16
	v_cndmask_b32_e32 v16, v16, v17, vcc
	v_mul_f32_e32 v17, 0xbfb8aa3b, v16
	v_mul_f32_e32 v19, v17, v0
	v_exp_f32_e32 v19, v19
	v_mul_f32_e32 v18, v17, v4
	v_exp_f32_e32 v18, v18
	v_mul_f32_e32 v16, v16, v16
	v_add_f32_e32 v19, 1.0, v19
	v_rcp_f32_e32 v20, v19
	v_mul_f32_e32 v19, v17, v5
	v_exp_f32_e32 v19, v19
	v_add_f32_e32 v18, 1.0, v18
	v_rcp_f32_e32 v18, v18
	v_pk_mul_f32 v[4:5], v[4:5], v[12:13]
	v_add_f32_e32 v19, 1.0, v19
	v_rcp_f32_e32 v19, v19
	s_and_b64 vcc, exec, s[38:39]
	v_pk_mul_f32 v[12:13], v[16:17], v[18:19] op_sel_hi:[0,1]
	v_pk_mul_f32 v[4:5], v[12:13], v[4:5]
	v_mul_f32_e32 v12, v17, v1
	v_exp_f32_e32 v12, v12
	v_pk_mul_f32 v[0:1], v[0:1], v[8:9]
	v_add_f32_e32 v12, 1.0, v12
	v_rcp_f32_e32 v21, v12
	v_add_u32_e32 v12, 0xb0, v154
	v_pk_mul_f32 v[8:9], v[16:17], v[20:21] op_sel_hi:[0,1]
	v_pk_mul_f32 v[8:9], v[8:9], v[0:1]
	v_mul_f32_e32 v1, v17, v2
	v_exp_f32_e32 v1, v1
	v_mul_f32_e32 v0, v17, v6
	v_exp_f32_e32 v0, v0
	v_add_f32_e32 v1, 1.0, v1
	v_rcp_f32_e32 v2, v1
	v_mul_f32_e32 v1, v17, v7
	v_exp_f32_e32 v1, v1
	v_add_f32_e32 v0, 1.0, v0
	v_rcp_f32_e32 v0, v0
	v_add_f32_e32 v1, 1.0, v1
	v_rcp_f32_e32 v1, v1
	s_nop 0
	v_pk_mul_f32 v[0:1], v[16:17], v[0:1] op_sel_hi:[0,1]
	v_pk_mul_f32 v[6:7], v[0:1], v[14:15]
	v_mul_f32_e32 v0, v17, v3
	v_exp_f32_e32 v0, v0
	s_nop 0
	v_add_f32_e32 v0, 1.0, v0
	v_rcp_f32_e32 v3, v0
	s_nop 0
	v_pk_mul_f32 v[0:1], v[16:17], v[2:3] op_sel_hi:[0,1]
	v_pk_mul_f32 v[10:11], v[0:1], v[10:11]
	v_cvt_pk_bf16_f32 v0, v4, v5
	v_mad_i64_i32 v[4:5], s[0:1], v12, s9, v[112:113]
	v_cvt_pk_bf16_f32 v1, v6, v7
	v_cvt_pk_bf16_f32 v2, v8, v9
	v_cvt_pk_bf16_f32 v3, v10, v11
	v_lshl_add_u64 v[4:5], v[4:5], 0, v[114:115]
	s_mov_b32 s0, s8
	global_store_dwordx4 v[4:5], v[0:3], off nt
	s_cbranch_vccz .LBB0_388
	s_waitcnt vmcnt(0)
	v_readlane_b32 s20, v255, 27
